# v9 plus GEMM K-loops issue LDS-DMA with SGPR base + 32-bit VGPR offset (no per-load 64-bit VALU adds)
# baseline (speedup 1.0000x reference)
; #define PG8_STAGE(bufoff, gbase, voff) do { _Pragma("unroll") for (int _i = 0; _i < 2; ++_i) \
;         __builtin_amdgcn_global_load_lds((const unsigned*)((const char*)(gbase) + (voff)[_i]), (LAS unsigned*)(lds + (bufoff) + ldsw + _i * 8192), 16, 0, 0); } while (0)
; #define PG8_LDA(dst, b, h) do { _Pragma("unroll") for (int m = 0; m < 4; ++m) _Pragma("unroll") for (int k = 0; k < 2; ++k) dst[m][k] = *(const LAS bf16x8*)(lds + PG8_SA(b, h) + aoff + m * 2048 + k * 1024); } while (0)
; #define PG8_LDB(dst, b, h) do { _Pragma("unroll") for (int n = 0; n < 2; ++n) _Pragma("unroll") for (int k = 0; k < 2; ++k) dst[n][k] = *(const LAS bf16x8*)(lds + PG8_SB(b, h) + boff + n * 2048 + k * 1024); } while (0)
; #define PG8_WAIT_V(n) asm volatile("s_waitcnt vmcnt(" #n ")" ::: "memory")
; #define PG8_BAR __builtin_amdgcn_s_barrier()
; template <class Epi, class Sched>
; __device__ __forceinline__ void gemm_phase(LAS unsigned char* lds, const Gemm g, const Sched& S, const Epi& E, const int tid) {
;     ...
;         for (int t = 0; t < nt; t += 2) {
;             const bool last = (t == nt - 2);
;             const char* a1 = cA + (size_t)(t + 1) * kstep;
;             const char* a2 = last ? nA : cA + (size_t)(t + 2) * kstep; const char* b2 = last ? nB : cB + (size_t)(t + 2) * kstep;
;             const char* a3 = a2 + kstep; const char* b3 = b2 + kstep;
;             PG8_LDB(B0, 0, 0); PG8_LDB(B1, 0, 1); PG8_SCHED; PG8_LDA(At, 0, 0); PG8_STAGE(PG8_SA(1, 1), a1 + hstepA, voffA);
;             PG8_WAIT_V(8); PG8_WAIT_L(0); PG8_BAR; PG8_MMA(0, 0, At, B0); PG8_MMA(0, 1, At, B1); PG8_BAR; PG8_SCHED;
;             PG8_LDA(At, 0, 1); PG8_STAGE(PG8_SB(0, 0), b2, voffB); PG8_STAGE(PG8_SB(0, 1), b2 + hstepB, voffB); PG8_STAGE(PG8_SA(0, 0), a2, voffA);
;             PG8_WAIT_V(8); PG8_WAIT_L(0); PG8_BAR; PG8_MMA(1, 0, At, B0); PG8_MMA(1, 1, At, B1); PG8_BAR; PG8_SCHED;
;             PG8_LDB(B0, 1, 0); PG8_LDB(B1, 1, 1); PG8_SCHED; PG8_LDA(At, 1, 0); PG8_STAGE(PG8_SA(0, 1), a2 + hstepA, voffA);
;             PG8_WAIT_V(8); PG8_WAIT_L(0); PG8_BAR; PG8_MMA(0, 0, At, B0); PG8_MMA(0, 1, At, B1); PG8_BAR; PG8_SCHED;
;             PG8_LDA(At, 1, 1); PG8_STAGE(PG8_SB(1, 0), b3, voffB); PG8_STAGE(PG8_SB(1, 1), b3 + hstepB, voffB); PG8_STAGE(PG8_SA(1, 0), a3, voffA);
;             PG8_WAIT_V(8); PG8_WAIT_L(0); PG8_BAR; PG8_MMA(1, 0, At, B0); PG8_MMA(1, 1, At, B1); PG8_BAR; PG8_SCHED;
.LBB1_36:
	s_add_u32 s42, s56, 0x100
	s_addc_u32 s43, s57, 0
	s_add_i32 s14, 0, 0x10000
	s_cmpk_eq_i32 s71, 0x54
	s_cselect_b32 s61, s49, s43
	s_cselect_b32 s60, s48, s42
	s_cselect_b32 s59, s53, s45
	s_cselect_b32 s58, s52, s44
	s_add_i32 s72, 0, 0x14000
	v_add_u32_e32 v142, s14, v213
	v_add_u32_e32 v158, s72, v213
	ds_read_b128 v[130:133], v142
	ds_read_b128 v[134:137], v142 offset:1024
	ds_read_b128 v[138:141], v142 offset:2048
	ds_read_b128 v[142:145], v142 offset:3072
	ds_read_b128 v[146:149], v158
	ds_read_b128 v[150:153], v158 offset:1024
	ds_read_b128 v[154:157], v158 offset:2048
	ds_read_b128 v[158:161], v158 offset:3072
	s_add_i32 m0, s47, 0xc000
	ds_read_b128 v[162:165], v218
	ds_read_b128 v[166:169], v218 offset:1024
	ds_read_b128 v[170:173], v218 offset:2048
	ds_read_b128 v[174:177], v218 offset:3072
	ds_read_b128 v[188:191], v218 offset:4096
	ds_read_b128 v[192:195], v218 offset:5120
	ds_read_b128 v[196:199], v218 offset:6144
	ds_read_b128 v[204:207], v218 offset:7168
	global_load_lds_dwordx4 v186, s[56:57]
	s_add_i32 m0, s47, 0xe000
	s_nop 0
	global_load_lds_dwordx4 v184, s[56:57]
	s_waitcnt vmcnt(8)
	s_waitcnt lgkmcnt(0)
	s_barrier
	s_setprio 1
	s_waitcnt lgkmcnt(0)
	v_mfma_f32_16x16x32_bf16 v[126:129], v[130:133], v[162:165], v[126:129]
	v_mfma_f32_16x16x32_bf16 v[122:125], v[138:141], v[162:165], v[122:125]
	v_mfma_f32_16x16x32_bf16 v[110:113], v[130:133], v[170:173], v[110:113]
	v_mfma_f32_16x16x32_bf16 v[106:109], v[138:141], v[170:173], v[106:109]
	v_mfma_f32_16x16x32_bf16 v[94:97], v[130:133], v[188:191], v[94:97]
	v_mfma_f32_16x16x32_bf16 v[90:93], v[138:141], v[188:191], v[90:93]
	v_mfma_f32_16x16x32_bf16 v[78:81], v[130:133], v[196:199], v[78:81]
	v_mfma_f32_16x16x32_bf16 v[74:77], v[138:141], v[196:199], v[74:77]
	v_mfma_f32_16x16x32_bf16 v[126:129], v[134:137], v[166:169], v[126:129]
	v_mfma_f32_16x16x32_bf16 v[122:125], v[142:145], v[166:169], v[122:125]
	v_mfma_f32_16x16x32_bf16 v[110:113], v[134:137], v[174:177], v[110:113]
	v_mfma_f32_16x16x32_bf16 v[106:109], v[142:145], v[174:177], v[106:109]
	v_mfma_f32_16x16x32_bf16 v[94:97], v[134:137], v[192:195], v[94:97]
	v_mfma_f32_16x16x32_bf16 v[90:93], v[142:145], v[192:195], v[90:93]
	v_mfma_f32_16x16x32_bf16 v[78:81], v[134:137], v[204:207], v[78:81]
	v_mfma_f32_16x16x32_bf16 v[74:77], v[142:145], v[204:207], v[74:77]
	s_setprio 0
	s_setprio 1
	v_mfma_f32_16x16x32_bf16 v[118:121], v[146:149], v[162:165], v[118:121]
	v_mfma_f32_16x16x32_bf16 v[114:117], v[154:157], v[162:165], v[114:117]
	v_mfma_f32_16x16x32_bf16 v[102:105], v[146:149], v[170:173], v[102:105]
	v_mfma_f32_16x16x32_bf16 v[98:101], v[154:157], v[170:173], v[98:101]
	v_mfma_f32_16x16x32_bf16 v[86:89], v[146:149], v[188:191], v[86:89]
	v_mfma_f32_16x16x32_bf16 v[82:85], v[154:157], v[188:191], v[82:85]
	v_mfma_f32_16x16x32_bf16 v[70:73], v[146:149], v[196:199], v[70:73]
	v_mfma_f32_16x16x32_bf16 v[66:69], v[154:157], v[196:199], v[66:69]
	v_mfma_f32_16x16x32_bf16 v[118:121], v[150:153], v[166:169], v[118:121]
	v_mfma_f32_16x16x32_bf16 v[114:117], v[158:161], v[166:169], v[114:117]
	v_mfma_f32_16x16x32_bf16 v[102:105], v[150:153], v[174:177], v[102:105]
	v_mfma_f32_16x16x32_bf16 v[98:101], v[158:161], v[174:177], v[98:101]
	v_mfma_f32_16x16x32_bf16 v[86:89], v[150:153], v[192:195], v[86:89]
	v_mfma_f32_16x16x32_bf16 v[82:85], v[158:161], v[192:195], v[82:85]
	v_mfma_f32_16x16x32_bf16 v[70:73], v[150:153], v[204:207], v[70:73]
	v_mfma_f32_16x16x32_bf16 v[66:69], v[158:161], v[204:207], v[66:69]
	s_setprio 0
	s_barrier
	s_add_i32 s14, s14, s46
	s_mov_b32 m0, s14
	ds_read_b128 v[162:165], v218 offset:16384
	ds_read_b128 v[166:169], v218 offset:17408
	ds_read_b128 v[170:173], v218 offset:18432
	ds_read_b128 v[174:177], v218 offset:19456
	ds_read_b128 v[188:191], v218 offset:20480
	ds_read_b128 v[192:195], v218 offset:21504
	ds_read_b128 v[196:199], v218 offset:22528
	ds_read_b128 v[204:207], v218 offset:23552
	global_load_lds_dwordx4 v0, s[58:59]
	s_add_i32 m0, s14, 0x2000
	s_add_u32 s14, s58, 0x160000
	s_addc_u32 s15, s59, 0
	s_add_i32 s56, s72, s46
	global_load_lds_dwordx4 v182, s[58:59]
	s_mov_b32 m0, s56
	s_nop 0
	global_load_lds_dwordx4 v0, s[14:15]
	s_add_i32 m0, s56, 0x2000
	s_nop 0
	global_load_lds_dwordx4 v182, s[14:15]
	s_mov_b32 m0, s47
	s_nop 0
	global_load_lds_dwordx4 v178, s[60:61]
	s_mov_b32 m0, s62
	s_nop 0
	global_load_lds_dwordx4 v180, s[60:61]
	s_waitcnt vmcnt(8)
	s_waitcnt lgkmcnt(0)
	s_barrier
	s_setprio 1
	s_waitcnt lgkmcnt(0)
	v_mfma_f32_16x16x32_bf16 v[62:65], v[130:133], v[162:165], v[62:65]
	v_mfma_f32_16x16x32_bf16 v[58:61], v[138:141], v[162:165], v[58:61]
	v_mfma_f32_16x16x32_bf16 v[46:49], v[130:133], v[170:173], v[46:49]
	v_mfma_f32_16x16x32_bf16 v[42:45], v[138:141], v[170:173], v[42:45]
	v_mfma_f32_16x16x32_bf16 v[30:33], v[130:133], v[188:191], v[30:33]
	v_mfma_f32_16x16x32_bf16 v[26:29], v[138:141], v[188:191], v[26:29]
	v_mfma_f32_16x16x32_bf16 v[14:17], v[130:133], v[196:199], v[14:17]
	v_mfma_f32_16x16x32_bf16 v[10:13], v[138:141], v[196:199], v[10:13]
	v_mfma_f32_16x16x32_bf16 v[62:65], v[134:137], v[166:169], v[62:65]
	v_mfma_f32_16x16x32_bf16 v[58:61], v[142:145], v[166:169], v[58:61]
	v_mfma_f32_16x16x32_bf16 v[46:49], v[134:137], v[174:177], v[46:49]
	v_mfma_f32_16x16x32_bf16 v[42:45], v[142:145], v[174:177], v[42:45]
	v_mfma_f32_16x16x32_bf16 v[30:33], v[134:137], v[192:195], v[30:33]
	v_mfma_f32_16x16x32_bf16 v[26:29], v[142:145], v[192:195], v[26:29]
	v_mfma_f32_16x16x32_bf16 v[14:17], v[134:137], v[204:207], v[14:17]
	v_mfma_f32_16x16x32_bf16 v[10:13], v[142:145], v[204:207], v[10:13]
	s_setprio 0
	s_setprio 1
	v_mfma_f32_16x16x32_bf16 v[54:57], v[146:149], v[162:165], v[54:57]
	v_mfma_f32_16x16x32_bf16 v[50:53], v[154:157], v[162:165], v[50:53]
	v_mfma_f32_16x16x32_bf16 v[38:41], v[146:149], v[170:173], v[38:41]
	v_mfma_f32_16x16x32_bf16 v[34:37], v[154:157], v[170:173], v[34:37]
	v_mfma_f32_16x16x32_bf16 v[22:25], v[146:149], v[188:191], v[22:25]
	v_mfma_f32_16x16x32_bf16 v[18:21], v[154:157], v[188:191], v[18:21]
	v_mfma_f32_16x16x32_bf16 v[6:9], v[146:149], v[196:199], v[6:9]
	v_mfma_f32_16x16x32_bf16 v[2:5], v[154:157], v[196:199], v[2:5]
	v_mfma_f32_16x16x32_bf16 v[54:57], v[150:153], v[166:169], v[54:57]
	v_mfma_f32_16x16x32_bf16 v[50:53], v[158:161], v[166:169], v[50:53]
	v_mfma_f32_16x16x32_bf16 v[38:41], v[150:153], v[174:177], v[38:41]
	v_mfma_f32_16x16x32_bf16 v[34:37], v[158:161], v[174:177], v[34:37]
	v_mfma_f32_16x16x32_bf16 v[22:25], v[150:153], v[192:195], v[22:25]
	v_mfma_f32_16x16x32_bf16 v[18:21], v[158:161], v[192:195], v[18:21]
	v_mfma_f32_16x16x32_bf16 v[6:9], v[150:153], v[204:207], v[6:9]
	v_mfma_f32_16x16x32_bf16 v[2:5], v[158:161], v[204:207], v[2:5]
	s_setprio 0
	s_barrier
; #define PG8_STAGE(bufoff, gbase, voff) do { _Pragma("unroll") for (int _i = 0; _i < 2; ++_i) \
;         __builtin_amdgcn_global_load_lds((const unsigned*)((const char*)(gbase) + (voff)[_i]), (LAS unsigned*)(lds + (bufoff) + ldsw + _i * 8192), 16, 0, 0); } while (0)
; #define PG8_LDA(dst, b, h) do { _Pragma("unroll") for (int m = 0; m < 4; ++m) _Pragma("unroll") for (int k = 0; k < 2; ++k) dst[m][k] = *(const LAS bf16x8*)(lds + PG8_SA(b, h) + aoff + m * 2048 + k * 1024); } while (0)
; #define PG8_LDB(dst, b, h) do { _Pragma("unroll") for (int n = 0; n < 2; ++n) _Pragma("unroll") for (int k = 0; k < 2; ++k) dst[n][k] = *(const LAS bf16x8*)(lds + PG8_SB(b, h) + boff + n * 2048 + k * 1024); } while (0)
; #define PG8_WAIT_V(n) asm volatile("s_waitcnt vmcnt(" #n ")" ::: "memory")
; template <class Epi, class Sched>
; __device__ __forceinline__ void gemm_phase(LAS unsigned char* lds, const Gemm g, const Sched& S, const Epi& E, const int tid) {
;     ...
;         for (int t = 0; t < nt; t += 2) {
;             const bool last = (t == nt - 2);
;             const char* a1 = cA + (size_t)(t + 1) * kstep;
;             const char* a2 = last ? nA : cA + (size_t)(t + 2) * kstep; const char* b2 = last ? nB : cB + (size_t)(t + 2) * kstep;
;             const char* a3 = a2 + kstep; const char* b3 = b2 + kstep;
;             PG8_LDB(B0, 0, 0); PG8_LDB(B1, 0, 1); PG8_SCHED; PG8_LDA(At, 0, 0); PG8_STAGE(PG8_SA(1, 1), a1 + hstepA, voffA);
;             PG8_WAIT_V(8); PG8_WAIT_L(0); PG8_BAR; PG8_MMA(0, 0, At, B0); PG8_MMA(0, 1, At, B1); PG8_BAR; PG8_SCHED;
;             PG8_LDA(At, 0, 1); PG8_STAGE(PG8_SB(0, 0), b2, voffB); PG8_STAGE(PG8_SB(0, 1), b2 + hstepB, voffB); PG8_STAGE(PG8_SA(0, 0), a2, voffA);
;             PG8_WAIT_V(8); PG8_WAIT_L(0); PG8_BAR; PG8_MMA(1, 0, At, B0); PG8_MMA(1, 1, At, B1); PG8_BAR; PG8_SCHED;
;             PG8_LDB(B0, 1, 0); PG8_LDB(B1, 1, 1); PG8_SCHED; PG8_LDA(At, 1, 0); PG8_STAGE(PG8_SA(0, 1), a2 + hstepA, voffA);
;             PG8_WAIT_V(8); PG8_WAIT_L(0); PG8_BAR; PG8_MMA(0, 0, At, B0); PG8_MMA(0, 1, At, B1); PG8_BAR; PG8_SCHED;
;             PG8_LDA(At, 1, 1); PG8_STAGE(PG8_SB(1, 0), b3, voffB); PG8_STAGE(PG8_SB(1, 1), b3 + hstepB, voffB); PG8_STAGE(PG8_SA(1, 0), a3, voffA);
;             PG8_WAIT_V(8); PG8_WAIT_L(0); PG8_BAR; PG8_MMA(1, 0, At, B0); PG8_MMA(1, 1, At, B1); PG8_BAR; PG8_SCHED;
;         }
;         if (wr == 0) PG8_BAR;
	s_add_i32 s56, 0, 0x18000
	s_add_i32 s57, 0, 0x1c000
	v_add_u32_e32 v142, s56, v213
	v_add_u32_e32 v158, s57, v213
	ds_read_b128 v[130:133], v142
	ds_read_b128 v[134:137], v142 offset:1024
	ds_read_b128 v[138:141], v142 offset:2048
	ds_read_b128 v[142:145], v142 offset:3072
	ds_read_b128 v[146:149], v158
	ds_read_b128 v[150:153], v158 offset:1024
	ds_read_b128 v[154:157], v158 offset:2048
	ds_read_b128 v[158:161], v158 offset:3072
	s_add_u32 s14, s60, 0x160000
	s_addc_u32 s15, s61, 0
	s_mov_b32 m0, s63
	ds_read_b128 v[162:165], v218 offset:32768
	ds_read_b128 v[166:169], v218 offset:33792
	ds_read_b128 v[170:173], v218 offset:34816
	ds_read_b128 v[174:177], v218 offset:35840
	ds_read_b128 v[188:191], v218 offset:36864
	ds_read_b128 v[192:195], v218 offset:37888
	ds_read_b128 v[196:199], v218 offset:38912
	ds_read_b128 v[204:207], v218 offset:39936
	global_load_lds_dwordx4 v178, s[14:15]
	s_mov_b32 m0, s64
	s_nop 0
	global_load_lds_dwordx4 v180, s[14:15]
	s_waitcnt vmcnt(8)
	s_waitcnt lgkmcnt(0)
	s_barrier
	s_setprio 1
	s_waitcnt lgkmcnt(0)
	v_mfma_f32_16x16x32_bf16 v[126:129], v[130:133], v[162:165], v[126:129]
	v_mfma_f32_16x16x32_bf16 v[122:125], v[138:141], v[162:165], v[122:125]
	v_mfma_f32_16x16x32_bf16 v[110:113], v[130:133], v[170:173], v[110:113]
	v_mfma_f32_16x16x32_bf16 v[106:109], v[138:141], v[170:173], v[106:109]
	v_mfma_f32_16x16x32_bf16 v[94:97], v[130:133], v[188:191], v[94:97]
	v_mfma_f32_16x16x32_bf16 v[90:93], v[138:141], v[188:191], v[90:93]
	v_mfma_f32_16x16x32_bf16 v[78:81], v[130:133], v[196:199], v[78:81]
	v_mfma_f32_16x16x32_bf16 v[74:77], v[138:141], v[196:199], v[74:77]
	v_mfma_f32_16x16x32_bf16 v[126:129], v[134:137], v[166:169], v[126:129]
	v_mfma_f32_16x16x32_bf16 v[122:125], v[142:145], v[166:169], v[122:125]
	v_mfma_f32_16x16x32_bf16 v[110:113], v[134:137], v[174:177], v[110:113]
	v_mfma_f32_16x16x32_bf16 v[106:109], v[142:145], v[174:177], v[106:109]
	v_mfma_f32_16x16x32_bf16 v[94:97], v[134:137], v[192:195], v[94:97]
	v_mfma_f32_16x16x32_bf16 v[90:93], v[142:145], v[192:195], v[90:93]
	v_mfma_f32_16x16x32_bf16 v[78:81], v[134:137], v[204:207], v[78:81]
	v_mfma_f32_16x16x32_bf16 v[74:77], v[142:145], v[204:207], v[74:77]
	s_setprio 0
	s_setprio 1
	v_mfma_f32_16x16x32_bf16 v[118:121], v[146:149], v[162:165], v[118:121]
	v_mfma_f32_16x16x32_bf16 v[114:117], v[154:157], v[162:165], v[114:117]
	v_mfma_f32_16x16x32_bf16 v[102:105], v[146:149], v[170:173], v[102:105]
	v_mfma_f32_16x16x32_bf16 v[98:101], v[154:157], v[170:173], v[98:101]
	v_mfma_f32_16x16x32_bf16 v[86:89], v[146:149], v[188:191], v[86:89]
	v_mfma_f32_16x16x32_bf16 v[82:85], v[154:157], v[188:191], v[82:85]
	v_mfma_f32_16x16x32_bf16 v[70:73], v[146:149], v[196:199], v[70:73]
	v_mfma_f32_16x16x32_bf16 v[66:69], v[154:157], v[196:199], v[66:69]
	v_mfma_f32_16x16x32_bf16 v[118:121], v[150:153], v[166:169], v[118:121]
	v_mfma_f32_16x16x32_bf16 v[114:117], v[158:161], v[166:169], v[114:117]
	v_mfma_f32_16x16x32_bf16 v[102:105], v[150:153], v[174:177], v[102:105]
	v_mfma_f32_16x16x32_bf16 v[98:101], v[158:161], v[174:177], v[98:101]
	v_mfma_f32_16x16x32_bf16 v[86:89], v[150:153], v[192:195], v[86:89]
	v_mfma_f32_16x16x32_bf16 v[82:85], v[158:161], v[192:195], v[82:85]
	v_mfma_f32_16x16x32_bf16 v[70:73], v[150:153], v[204:207], v[70:73]
	v_mfma_f32_16x16x32_bf16 v[66:69], v[158:161], v[204:207], v[66:69]
	s_setprio 0
	s_barrier
	s_add_i32 s14, s56, s46
	s_add_u32 s100, s58, 0x80
	s_addc_u32 s101, s59, 0
	s_mov_b32 m0, s14
	ds_read_b128 v[162:165], v218 offset:49152
	ds_read_b128 v[166:169], v218 offset:50176
	ds_read_b128 v[170:173], v218 offset:51200
	ds_read_b128 v[174:177], v218 offset:52224
	ds_read_b128 v[188:191], v218 offset:53248
	ds_read_b128 v[192:195], v218 offset:54272
	ds_read_b128 v[196:199], v218 offset:55296
	ds_read_b128 v[204:207], v218 offset:56320
	global_load_lds_dwordx4 v0, s[100:101]
	s_add_i32 m0, s14, 0x2000
	s_add_u32 s14, s58, 0x160080
	s_addc_u32 s15, s59, 0
	s_add_i32 s56, s57, s46
	global_load_lds_dwordx4 v182, s[100:101]
	s_mov_b32 m0, s56
	s_nop 0
	global_load_lds_dwordx4 v0, s[14:15]
	s_add_i32 m0, s56, 0x2000
	s_nop 0
	global_load_lds_dwordx4 v182, s[14:15]
	s_add_u32 s100, s60, 0x80
	s_addc_u32 s101, s61, 0
	s_mov_b32 m0, s65
	s_nop 0
	global_load_lds_dwordx4 v178, s[100:101]
	s_mov_b32 m0, s66
	s_nop 0
	global_load_lds_dwordx4 v180, s[100:101]
	s_waitcnt vmcnt(8)
	s_waitcnt lgkmcnt(0)
	s_barrier
	s_setprio 1
	s_waitcnt lgkmcnt(0)
	v_mfma_f32_16x16x32_bf16 v[62:65], v[130:133], v[162:165], v[62:65]
	v_mfma_f32_16x16x32_bf16 v[58:61], v[138:141], v[162:165], v[58:61]
	v_mfma_f32_16x16x32_bf16 v[46:49], v[130:133], v[170:173], v[46:49]
	v_mfma_f32_16x16x32_bf16 v[42:45], v[138:141], v[170:173], v[42:45]
	v_mfma_f32_16x16x32_bf16 v[30:33], v[130:133], v[188:191], v[30:33]
	v_mfma_f32_16x16x32_bf16 v[26:29], v[138:141], v[188:191], v[26:29]
	v_mfma_f32_16x16x32_bf16 v[14:17], v[130:133], v[196:199], v[14:17]
	v_mfma_f32_16x16x32_bf16 v[10:13], v[138:141], v[196:199], v[10:13]
	v_mfma_f32_16x16x32_bf16 v[62:65], v[134:137], v[166:169], v[62:65]
	v_mfma_f32_16x16x32_bf16 v[58:61], v[142:145], v[166:169], v[58:61]
	v_mfma_f32_16x16x32_bf16 v[46:49], v[134:137], v[174:177], v[46:49]
	v_mfma_f32_16x16x32_bf16 v[42:45], v[142:145], v[174:177], v[42:45]
	v_mfma_f32_16x16x32_bf16 v[30:33], v[134:137], v[192:195], v[30:33]
	v_mfma_f32_16x16x32_bf16 v[26:29], v[142:145], v[192:195], v[26:29]
	v_mfma_f32_16x16x32_bf16 v[14:17], v[134:137], v[204:207], v[14:17]
	v_mfma_f32_16x16x32_bf16 v[10:13], v[142:145], v[204:207], v[10:13]
	s_setprio 0
	s_setprio 1
	v_mfma_f32_16x16x32_bf16 v[54:57], v[146:149], v[162:165], v[54:57]
	v_mfma_f32_16x16x32_bf16 v[50:53], v[154:157], v[162:165], v[50:53]
	v_mfma_f32_16x16x32_bf16 v[38:41], v[146:149], v[170:173], v[38:41]
	v_mfma_f32_16x16x32_bf16 v[34:37], v[154:157], v[170:173], v[34:37]
	v_mfma_f32_16x16x32_bf16 v[22:25], v[146:149], v[188:191], v[22:25]
	v_mfma_f32_16x16x32_bf16 v[18:21], v[154:157], v[188:191], v[18:21]
	v_mfma_f32_16x16x32_bf16 v[6:9], v[146:149], v[196:199], v[6:9]
	v_mfma_f32_16x16x32_bf16 v[2:5], v[154:157], v[196:199], v[2:5]
	v_mfma_f32_16x16x32_bf16 v[54:57], v[150:153], v[166:169], v[54:57]
	v_mfma_f32_16x16x32_bf16 v[50:53], v[158:161], v[166:169], v[50:53]
	v_mfma_f32_16x16x32_bf16 v[38:41], v[150:153], v[174:177], v[38:41]
	v_mfma_f32_16x16x32_bf16 v[34:37], v[158:161], v[174:177], v[34:37]
	v_mfma_f32_16x16x32_bf16 v[22:25], v[150:153], v[192:195], v[22:25]
	v_mfma_f32_16x16x32_bf16 v[18:21], v[158:161], v[192:195], v[18:21]
	v_mfma_f32_16x16x32_bf16 v[6:9], v[150:153], v[204:207], v[6:9]
	v_mfma_f32_16x16x32_bf16 v[2:5], v[158:161], v[204:207], v[2:5]
	s_setprio 0
	s_barrier
	s_add_i32 s71, s71, 2
	s_add_u32 s44, s44, 0x100
	s_addc_u32 s45, s45, 0
	s_cmpk_gt_u32 s71, 0x55
	s_mov_b64 s[56:57], s[42:43]
	s_cbranch_scc0 .LBB1_36
	s_and_b64 vcc, exec, s[36:37]
	s_cbranch_vccz .LBB1_39
	s_barrier

; #define PG8_STAGE(bufoff, gbase, voff) do { _Pragma("unroll") for (int _i = 0; _i < 2; ++_i) \
;         __builtin_amdgcn_global_load_lds((const unsigned*)((const char*)(gbase) + (voff)[_i]), (LAS unsigned*)(lds + (bufoff) + ldsw + _i * 8192), 16, 0, 0); } while (0)
; #define PG8_LDA(dst, b, h) do { _Pragma("unroll") for (int m = 0; m < 4; ++m) _Pragma("unroll") for (int k = 0; k < 2; ++k) dst[m][k] = *(const LAS bf16x8*)(lds + PG8_SA(b, h) + aoff + m * 2048 + k * 1024); } while (0)
; #define PG8_LDB(dst, b, h) do { _Pragma("unroll") for (int n = 0; n < 2; ++n) _Pragma("unroll") for (int k = 0; k < 2; ++k) dst[n][k] = *(const LAS bf16x8*)(lds + PG8_SB(b, h) + boff + n * 2048 + k * 1024); } while (0)
; #define PG8_WAIT_V(n) asm volatile("s_waitcnt vmcnt(" #n ")" ::: "memory")
; #define PG8_BAR __builtin_amdgcn_s_barrier()
; template <class Epi, class Sched>
; __device__ __forceinline__ void gemm_phase(LAS unsigned char* lds, const Gemm g, const Sched& S, const Epi& E, const int tid) {
;     ...
;         for (int t = 0; t < nt; t += 2) {
;             const bool last = (t == nt - 2);
;             const char* a1 = cA + (size_t)(t + 1) * kstep;
;             const char* a2 = last ? nA : cA + (size_t)(t + 2) * kstep; const char* b2 = last ? nB : cB + (size_t)(t + 2) * kstep;
;             const char* a3 = a2 + kstep; const char* b3 = b2 + kstep;
;             PG8_LDB(B0, 0, 0); PG8_LDB(B1, 0, 1); PG8_SCHED; PG8_LDA(At, 0, 0); PG8_STAGE(PG8_SA(1, 1), a1 + hstepA, voffA);
;             PG8_WAIT_V(8); PG8_WAIT_L(0); PG8_BAR; PG8_MMA(0, 0, At, B0); PG8_MMA(0, 1, At, B1); PG8_BAR; PG8_SCHED;
;             PG8_LDA(At, 0, 1); PG8_STAGE(PG8_SB(0, 0), b2, voffB); PG8_STAGE(PG8_SB(0, 1), b2 + hstepB, voffB); PG8_STAGE(PG8_SA(0, 0), a2, voffA);
;             PG8_WAIT_V(8); PG8_WAIT_L(0); PG8_BAR; PG8_MMA(1, 0, At, B0); PG8_MMA(1, 1, At, B1); PG8_BAR; PG8_SCHED;
;             PG8_LDB(B0, 1, 0); PG8_LDB(B1, 1, 1); PG8_SCHED; PG8_LDA(At, 1, 0); PG8_STAGE(PG8_SA(0, 1), a2 + hstepA, voffA);
;             PG8_WAIT_V(8); PG8_WAIT_L(0); PG8_BAR; PG8_MMA(0, 0, At, B0); PG8_MMA(0, 1, At, B1); PG8_BAR; PG8_SCHED;
;             PG8_LDA(At, 1, 1); PG8_STAGE(PG8_SB(1, 0), b3, voffB); PG8_STAGE(PG8_SB(1, 1), b3 + hstepB, voffB); PG8_STAGE(PG8_SA(1, 0), a3, voffA);
;             PG8_WAIT_V(8); PG8_WAIT_L(0); PG8_BAR; PG8_MMA(1, 0, At, B0); PG8_MMA(1, 1, At, B1); PG8_BAR; PG8_SCHED;
.LBB1_87:
	s_add_u32 s14, s58, 0xfff80080
	s_addc_u32 s15, s59, -1
	s_add_i32 s70, 0, 0x10000
	s_cmp_eq_u32 s45, 28
	s_cselect_b32 s63, s37, s15
	s_cselect_b32 s62, s53, s14
	v_add_u32_e32 v144, s70, v147
	s_cselect_b32 s61, s41, s44
	s_cselect_b32 s60, s68, s69
	s_add_i32 s71, 0, 0x14000
	ds_read_b128 v[140:143], v144
	ds_read_b128 v[158:161], v144 offset:1024
	ds_read_b128 v[162:165], v144 offset:2048
	ds_read_b128 v[166:169], v144 offset:3072
	v_add_u32_e32 v144, s71, v147
	ds_read_b128 v[170:173], v144
	ds_read_b128 v[174:177], v144 offset:1024
	ds_read_b128 v[178:181], v144 offset:2048
	ds_read_b128 v[182:185], v144 offset:3072
	s_add_i32 m0, s47, 0xc000
	ds_read_b128 v[186:189], v157
	ds_read_b128 v[190:193], v157 offset:1024
	ds_read_b128 v[194:197], v157 offset:2048
	ds_read_b128 v[198:201], v157 offset:3072
	ds_read_b128 v[204:207], v157 offset:4096
	ds_read_b128 v[208:211], v157 offset:5120
	ds_read_b128 v[212:215], v157 offset:6144
	ds_read_b128 v[216:219], v157 offset:7168
	global_load_lds_dwordx4 v138, s[58:59]
	s_add_i32 m0, s47, 0xe000
	s_nop 0
	global_load_lds_dwordx4 v136, s[58:59]
	s_waitcnt vmcnt(8)
	s_waitcnt lgkmcnt(0)
	s_barrier
	s_setprio 1
	s_waitcnt lgkmcnt(0)
	v_mfma_f32_16x16x32_bf16 v[126:129], v[140:143], v[186:189], v[126:129]
	v_mfma_f32_16x16x32_bf16 v[118:121], v[162:165], v[186:189], v[118:121]
	v_mfma_f32_16x16x32_bf16 v[110:113], v[140:143], v[194:197], v[110:113]
	v_mfma_f32_16x16x32_bf16 v[106:109], v[162:165], v[194:197], v[106:109]
	v_mfma_f32_16x16x32_bf16 v[94:97], v[140:143], v[204:207], v[94:97]
	v_mfma_f32_16x16x32_bf16 v[90:93], v[162:165], v[204:207], v[90:93]
	v_mfma_f32_16x16x32_bf16 v[78:81], v[140:143], v[212:215], v[78:81]
	v_mfma_f32_16x16x32_bf16 v[74:77], v[162:165], v[212:215], v[74:77]
	v_mfma_f32_16x16x32_bf16 v[126:129], v[158:161], v[190:193], v[126:129]
	v_mfma_f32_16x16x32_bf16 v[118:121], v[166:169], v[190:193], v[118:121]
	v_mfma_f32_16x16x32_bf16 v[110:113], v[158:161], v[198:201], v[110:113]
	v_mfma_f32_16x16x32_bf16 v[106:109], v[166:169], v[198:201], v[106:109]
	v_mfma_f32_16x16x32_bf16 v[94:97], v[158:161], v[208:211], v[94:97]
	v_mfma_f32_16x16x32_bf16 v[90:93], v[166:169], v[208:211], v[90:93]
	v_mfma_f32_16x16x32_bf16 v[78:81], v[158:161], v[216:219], v[78:81]
	v_mfma_f32_16x16x32_bf16 v[74:77], v[166:169], v[216:219], v[74:77]
	s_setprio 0
	s_setprio 1
	v_mfma_f32_16x16x32_bf16 v[122:125], v[170:173], v[186:189], v[122:125]
	v_mfma_f32_16x16x32_bf16 v[114:117], v[178:181], v[186:189], v[114:117]
	v_mfma_f32_16x16x32_bf16 v[102:105], v[170:173], v[194:197], v[102:105]
	v_mfma_f32_16x16x32_bf16 v[98:101], v[178:181], v[194:197], v[98:101]
	v_mfma_f32_16x16x32_bf16 v[86:89], v[170:173], v[204:207], v[86:89]
	v_mfma_f32_16x16x32_bf16 v[82:85], v[178:181], v[204:207], v[82:85]
	v_mfma_f32_16x16x32_bf16 v[70:73], v[170:173], v[212:215], v[70:73]
	v_mfma_f32_16x16x32_bf16 v[66:69], v[178:181], v[212:215], v[66:69]
	v_mfma_f32_16x16x32_bf16 v[122:125], v[174:177], v[190:193], v[122:125]
	v_mfma_f32_16x16x32_bf16 v[114:117], v[182:185], v[190:193], v[114:117]
	v_mfma_f32_16x16x32_bf16 v[102:105], v[174:177], v[198:201], v[102:105]
	v_mfma_f32_16x16x32_bf16 v[98:101], v[182:185], v[198:201], v[98:101]
	v_mfma_f32_16x16x32_bf16 v[86:89], v[174:177], v[208:211], v[86:89]
	v_mfma_f32_16x16x32_bf16 v[82:85], v[182:185], v[208:211], v[82:85]
	v_mfma_f32_16x16x32_bf16 v[70:73], v[174:177], v[216:219], v[70:73]
	v_mfma_f32_16x16x32_bf16 v[66:69], v[182:185], v[216:219], v[66:69]
	s_setprio 0
	s_barrier
	s_add_i32 s14, s70, s46
	s_mov_b32 m0, s14
	ds_read_b128 v[186:189], v157 offset:16384
	ds_read_b128 v[190:193], v157 offset:17408
	ds_read_b128 v[194:197], v157 offset:18432
	ds_read_b128 v[198:201], v157 offset:19456
	ds_read_b128 v[204:207], v157 offset:20480
	ds_read_b128 v[208:211], v157 offset:21504
	ds_read_b128 v[212:215], v157 offset:22528
	ds_read_b128 v[216:219], v157 offset:23552
	global_load_lds_dwordx4 v0, s[60:61]
	s_add_i32 m0, s14, 0x2000
	s_add_u32 s14, s60, 0x80000
	s_addc_u32 s15, s61, 0
	s_add_i32 s70, s71, s46
	global_load_lds_dwordx4 v130, s[60:61]
	s_mov_b32 m0, s70
	s_nop 0
	global_load_lds_dwordx4 v0, s[14:15]
	s_add_i32 m0, s70, 0x2000
	s_nop 0
	global_load_lds_dwordx4 v130, s[14:15]
	s_mov_b32 m0, s47
	s_nop 0
	global_load_lds_dwordx4 v134, s[62:63]
	s_mov_b32 m0, s57
	s_nop 0
	global_load_lds_dwordx4 v132, s[62:63]
	s_waitcnt vmcnt(8)
	s_waitcnt lgkmcnt(0)
	s_barrier
	s_setprio 1
	s_waitcnt lgkmcnt(0)
	v_mfma_f32_16x16x32_bf16 v[62:65], v[140:143], v[186:189], v[62:65]
	v_mfma_f32_16x16x32_bf16 v[58:61], v[162:165], v[186:189], v[58:61]
	v_mfma_f32_16x16x32_bf16 v[46:49], v[140:143], v[194:197], v[46:49]
	v_mfma_f32_16x16x32_bf16 v[42:45], v[162:165], v[194:197], v[42:45]
	v_mfma_f32_16x16x32_bf16 v[30:33], v[140:143], v[204:207], v[30:33]
	v_mfma_f32_16x16x32_bf16 v[26:29], v[162:165], v[204:207], v[26:29]
	v_mfma_f32_16x16x32_bf16 v[14:17], v[140:143], v[212:215], v[14:17]
	v_mfma_f32_16x16x32_bf16 v[10:13], v[162:165], v[212:215], v[10:13]
	v_mfma_f32_16x16x32_bf16 v[62:65], v[158:161], v[190:193], v[62:65]
	v_mfma_f32_16x16x32_bf16 v[58:61], v[166:169], v[190:193], v[58:61]
	v_mfma_f32_16x16x32_bf16 v[46:49], v[158:161], v[198:201], v[46:49]
	v_mfma_f32_16x16x32_bf16 v[42:45], v[166:169], v[198:201], v[42:45]
	v_mfma_f32_16x16x32_bf16 v[30:33], v[158:161], v[208:211], v[30:33]
	v_mfma_f32_16x16x32_bf16 v[26:29], v[166:169], v[208:211], v[26:29]
	v_mfma_f32_16x16x32_bf16 v[14:17], v[158:161], v[216:219], v[14:17]
	v_mfma_f32_16x16x32_bf16 v[10:13], v[166:169], v[216:219], v[10:13]
	s_setprio 0
	s_setprio 1
	v_mfma_f32_16x16x32_bf16 v[54:57], v[170:173], v[186:189], v[54:57]
	v_mfma_f32_16x16x32_bf16 v[50:53], v[178:181], v[186:189], v[50:53]
	v_mfma_f32_16x16x32_bf16 v[38:41], v[170:173], v[194:197], v[38:41]
	v_mfma_f32_16x16x32_bf16 v[34:37], v[178:181], v[194:197], v[34:37]
	v_mfma_f32_16x16x32_bf16 v[22:25], v[170:173], v[204:207], v[22:25]
	v_mfma_f32_16x16x32_bf16 v[18:21], v[178:181], v[204:207], v[18:21]
	v_mfma_f32_16x16x32_bf16 v[6:9], v[170:173], v[212:215], v[6:9]
	v_mfma_f32_16x16x32_bf16 v[2:5], v[178:181], v[212:215], v[2:5]
	v_mfma_f32_16x16x32_bf16 v[54:57], v[174:177], v[190:193], v[54:57]
	v_mfma_f32_16x16x32_bf16 v[50:53], v[182:185], v[190:193], v[50:53]
	v_mfma_f32_16x16x32_bf16 v[38:41], v[174:177], v[198:201], v[38:41]
	v_mfma_f32_16x16x32_bf16 v[34:37], v[182:185], v[198:201], v[34:37]
	v_mfma_f32_16x16x32_bf16 v[22:25], v[174:177], v[208:211], v[22:25]
	v_mfma_f32_16x16x32_bf16 v[18:21], v[182:185], v[208:211], v[18:21]
	v_mfma_f32_16x16x32_bf16 v[6:9], v[174:177], v[216:219], v[6:9]
	v_mfma_f32_16x16x32_bf16 v[2:5], v[182:185], v[216:219], v[2:5]
	s_setprio 0
	s_barrier
; #define PG8_STAGE(bufoff, gbase, voff) do { _Pragma("unroll") for (int _i = 0; _i < 2; ++_i) \
;         __builtin_amdgcn_global_load_lds((const unsigned*)((const char*)(gbase) + (voff)[_i]), (LAS unsigned*)(lds + (bufoff) + ldsw + _i * 8192), 16, 0, 0); } while (0)
; #define PG8_LDA(dst, b, h) do { _Pragma("unroll") for (int m = 0; m < 4; ++m) _Pragma("unroll") for (int k = 0; k < 2; ++k) dst[m][k] = *(const LAS bf16x8*)(lds + PG8_SA(b, h) + aoff + m * 2048 + k * 1024); } while (0)
; #define PG8_LDB(dst, b, h) do { _Pragma("unroll") for (int n = 0; n < 2; ++n) _Pragma("unroll") for (int k = 0; k < 2; ++k) dst[n][k] = *(const LAS bf16x8*)(lds + PG8_SB(b, h) + boff + n * 2048 + k * 1024); } while (0)
; #define PG8_WAIT_V(n) asm volatile("s_waitcnt vmcnt(" #n ")" ::: "memory")
; template <class Epi, class Sched>
; __device__ __forceinline__ void gemm_phase(LAS unsigned char* lds, const Gemm g, const Sched& S, const Epi& E, const int tid) {
;     ...
;         for (int t = 0; t < nt; t += 2) {
;             const bool last = (t == nt - 2);
;             const char* a1 = cA + (size_t)(t + 1) * kstep;
;             const char* a2 = last ? nA : cA + (size_t)(t + 2) * kstep; const char* b2 = last ? nB : cB + (size_t)(t + 2) * kstep;
;             const char* a3 = a2 + kstep; const char* b3 = b2 + kstep;
;             PG8_LDB(B0, 0, 0); PG8_LDB(B1, 0, 1); PG8_SCHED; PG8_LDA(At, 0, 0); PG8_STAGE(PG8_SA(1, 1), a1 + hstepA, voffA);
;             PG8_WAIT_V(8); PG8_WAIT_L(0); PG8_BAR; PG8_MMA(0, 0, At, B0); PG8_MMA(0, 1, At, B1); PG8_BAR; PG8_SCHED;
;             PG8_LDA(At, 0, 1); PG8_STAGE(PG8_SB(0, 0), b2, voffB); PG8_STAGE(PG8_SB(0, 1), b2 + hstepB, voffB); PG8_STAGE(PG8_SA(0, 0), a2, voffA);
;             PG8_WAIT_V(8); PG8_WAIT_L(0); PG8_BAR; PG8_MMA(1, 0, At, B0); PG8_MMA(1, 1, At, B1); PG8_BAR; PG8_SCHED;
;             PG8_LDB(B0, 1, 0); PG8_LDB(B1, 1, 1); PG8_SCHED; PG8_LDA(At, 1, 0); PG8_STAGE(PG8_SA(0, 1), a2 + hstepA, voffA);
;             PG8_WAIT_V(8); PG8_WAIT_L(0); PG8_BAR; PG8_MMA(0, 0, At, B0); PG8_MMA(0, 1, At, B1); PG8_BAR; PG8_SCHED;
;             PG8_LDA(At, 1, 1); PG8_STAGE(PG8_SB(1, 0), b3, voffB); PG8_STAGE(PG8_SB(1, 1), b3 + hstepB, voffB); PG8_STAGE(PG8_SA(1, 0), a3, voffA);
;             PG8_WAIT_V(8); PG8_WAIT_L(0); PG8_BAR; PG8_MMA(1, 0, At, B0); PG8_MMA(1, 1, At, B1); PG8_BAR; PG8_SCHED;
;         }
;         if (wr == 0) PG8_BAR;
	s_add_i32 s70, 0, 0x18000
	v_add_u32_e32 v144, s70, v147
	s_add_i32 s71, 0, 0x1c000
	ds_read_b128 v[140:143], v144
	ds_read_b128 v[158:161], v144 offset:1024
	ds_read_b128 v[162:165], v144 offset:2048
	ds_read_b128 v[166:169], v144 offset:3072
	v_add_u32_e32 v144, s71, v147
	ds_read_b128 v[170:173], v144
	ds_read_b128 v[174:177], v144 offset:1024
	ds_read_b128 v[178:181], v144 offset:2048
	ds_read_b128 v[182:185], v144 offset:3072
	s_add_u32 s14, s62, 0x80000
	s_addc_u32 s15, s63, 0
	s_mov_b32 m0, s64
	ds_read_b128 v[186:189], v157 offset:32768
	ds_read_b128 v[190:193], v157 offset:33792
	ds_read_b128 v[194:197], v157 offset:34816
	ds_read_b128 v[198:201], v157 offset:35840
	ds_read_b128 v[204:207], v157 offset:36864
	ds_read_b128 v[208:211], v157 offset:37888
	ds_read_b128 v[212:215], v157 offset:38912
	ds_read_b128 v[216:219], v157 offset:39936
	global_load_lds_dwordx4 v134, s[14:15]
	s_mov_b32 m0, s65
	s_nop 0
	global_load_lds_dwordx4 v132, s[14:15]
	s_waitcnt vmcnt(8)
	s_waitcnt lgkmcnt(0)
	s_barrier
	s_setprio 1
	s_waitcnt lgkmcnt(0)
	v_mfma_f32_16x16x32_bf16 v[126:129], v[140:143], v[186:189], v[126:129]
	v_mfma_f32_16x16x32_bf16 v[118:121], v[162:165], v[186:189], v[118:121]
	v_mfma_f32_16x16x32_bf16 v[110:113], v[140:143], v[194:197], v[110:113]
	v_mfma_f32_16x16x32_bf16 v[106:109], v[162:165], v[194:197], v[106:109]
	v_mfma_f32_16x16x32_bf16 v[94:97], v[140:143], v[204:207], v[94:97]
	v_mfma_f32_16x16x32_bf16 v[90:93], v[162:165], v[204:207], v[90:93]
	v_mfma_f32_16x16x32_bf16 v[78:81], v[140:143], v[212:215], v[78:81]
	v_mfma_f32_16x16x32_bf16 v[74:77], v[162:165], v[212:215], v[74:77]
	v_mfma_f32_16x16x32_bf16 v[126:129], v[158:161], v[190:193], v[126:129]
	v_mfma_f32_16x16x32_bf16 v[118:121], v[166:169], v[190:193], v[118:121]
	v_mfma_f32_16x16x32_bf16 v[110:113], v[158:161], v[198:201], v[110:113]
	v_mfma_f32_16x16x32_bf16 v[106:109], v[166:169], v[198:201], v[106:109]
	v_mfma_f32_16x16x32_bf16 v[94:97], v[158:161], v[208:211], v[94:97]
	v_mfma_f32_16x16x32_bf16 v[90:93], v[166:169], v[208:211], v[90:93]
	v_mfma_f32_16x16x32_bf16 v[78:81], v[158:161], v[216:219], v[78:81]
	v_mfma_f32_16x16x32_bf16 v[74:77], v[166:169], v[216:219], v[74:77]
	s_setprio 0
	s_setprio 1
	v_mfma_f32_16x16x32_bf16 v[122:125], v[170:173], v[186:189], v[122:125]
	v_mfma_f32_16x16x32_bf16 v[114:117], v[178:181], v[186:189], v[114:117]
	v_mfma_f32_16x16x32_bf16 v[102:105], v[170:173], v[194:197], v[102:105]
	v_mfma_f32_16x16x32_bf16 v[98:101], v[178:181], v[194:197], v[98:101]
	v_mfma_f32_16x16x32_bf16 v[86:89], v[170:173], v[204:207], v[86:89]
	v_mfma_f32_16x16x32_bf16 v[82:85], v[178:181], v[204:207], v[82:85]
	v_mfma_f32_16x16x32_bf16 v[70:73], v[170:173], v[212:215], v[70:73]
	v_mfma_f32_16x16x32_bf16 v[66:69], v[178:181], v[212:215], v[66:69]
	v_mfma_f32_16x16x32_bf16 v[122:125], v[174:177], v[190:193], v[122:125]
	v_mfma_f32_16x16x32_bf16 v[114:117], v[182:185], v[190:193], v[114:117]
	v_mfma_f32_16x16x32_bf16 v[102:105], v[174:177], v[198:201], v[102:105]
	v_mfma_f32_16x16x32_bf16 v[98:101], v[182:185], v[198:201], v[98:101]
	v_mfma_f32_16x16x32_bf16 v[86:89], v[174:177], v[208:211], v[86:89]
	v_mfma_f32_16x16x32_bf16 v[82:85], v[182:185], v[208:211], v[82:85]
	v_mfma_f32_16x16x32_bf16 v[70:73], v[174:177], v[216:219], v[70:73]
	v_mfma_f32_16x16x32_bf16 v[66:69], v[182:185], v[216:219], v[66:69]
	s_setprio 0
	s_barrier
	s_add_i32 s14, s70, s46
	s_add_u32 s100, s60, 0x80
	s_addc_u32 s101, s61, 0
	s_mov_b32 m0, s14
	ds_read_b128 v[186:189], v157 offset:49152
	ds_read_b128 v[190:193], v157 offset:50176
	ds_read_b128 v[194:197], v157 offset:51200
	ds_read_b128 v[198:201], v157 offset:52224
	ds_read_b128 v[204:207], v157 offset:53248
	ds_read_b128 v[208:211], v157 offset:54272
	ds_read_b128 v[212:215], v157 offset:55296
	ds_read_b128 v[216:219], v157 offset:56320
	global_load_lds_dwordx4 v0, s[100:101]
	s_add_i32 m0, s14, 0x2000
	s_add_u32 s14, s60, 0x80080
	s_addc_u32 s15, s61, 0
	s_add_i32 s60, s71, s46
	global_load_lds_dwordx4 v130, s[100:101]
	s_mov_b32 m0, s60
	s_nop 0
	global_load_lds_dwordx4 v0, s[14:15]
	s_add_i32 m0, s60, 0x2000
	s_nop 0
	global_load_lds_dwordx4 v130, s[14:15]
	s_add_u32 s100, s62, 0x80
	s_addc_u32 s101, s63, 0
	s_mov_b32 m0, s66
	s_nop 0
	global_load_lds_dwordx4 v134, s[100:101]
	s_mov_b32 m0, s67
	s_nop 0
	global_load_lds_dwordx4 v132, s[100:101]
	s_waitcnt vmcnt(8)
	s_waitcnt lgkmcnt(0)
	s_barrier
	s_setprio 1
	s_waitcnt lgkmcnt(0)
	v_mfma_f32_16x16x32_bf16 v[62:65], v[140:143], v[186:189], v[62:65]
	v_mfma_f32_16x16x32_bf16 v[58:61], v[162:165], v[186:189], v[58:61]
	v_mfma_f32_16x16x32_bf16 v[46:49], v[140:143], v[194:197], v[46:49]
	v_mfma_f32_16x16x32_bf16 v[42:45], v[162:165], v[194:197], v[42:45]
	v_mfma_f32_16x16x32_bf16 v[30:33], v[140:143], v[204:207], v[30:33]
	v_mfma_f32_16x16x32_bf16 v[26:29], v[162:165], v[204:207], v[26:29]
	v_mfma_f32_16x16x32_bf16 v[14:17], v[140:143], v[212:215], v[14:17]
	v_mfma_f32_16x16x32_bf16 v[10:13], v[162:165], v[212:215], v[10:13]
	v_mfma_f32_16x16x32_bf16 v[62:65], v[158:161], v[190:193], v[62:65]
	v_mfma_f32_16x16x32_bf16 v[58:61], v[166:169], v[190:193], v[58:61]
	v_mfma_f32_16x16x32_bf16 v[46:49], v[158:161], v[198:201], v[46:49]
	v_mfma_f32_16x16x32_bf16 v[42:45], v[166:169], v[198:201], v[42:45]
	v_mfma_f32_16x16x32_bf16 v[30:33], v[158:161], v[208:211], v[30:33]
	v_mfma_f32_16x16x32_bf16 v[26:29], v[166:169], v[208:211], v[26:29]
	v_mfma_f32_16x16x32_bf16 v[14:17], v[158:161], v[216:219], v[14:17]
	v_mfma_f32_16x16x32_bf16 v[10:13], v[166:169], v[216:219], v[10:13]
	s_setprio 0
	s_setprio 1
	v_mfma_f32_16x16x32_bf16 v[54:57], v[170:173], v[186:189], v[54:57]
	v_mfma_f32_16x16x32_bf16 v[50:53], v[178:181], v[186:189], v[50:53]
	v_mfma_f32_16x16x32_bf16 v[38:41], v[170:173], v[194:197], v[38:41]
	v_mfma_f32_16x16x32_bf16 v[34:37], v[178:181], v[194:197], v[34:37]
	v_mfma_f32_16x16x32_bf16 v[22:25], v[170:173], v[204:207], v[22:25]
	v_mfma_f32_16x16x32_bf16 v[18:21], v[178:181], v[204:207], v[18:21]
	v_mfma_f32_16x16x32_bf16 v[6:9], v[170:173], v[212:215], v[6:9]
	v_mfma_f32_16x16x32_bf16 v[2:5], v[178:181], v[212:215], v[2:5]
	v_mfma_f32_16x16x32_bf16 v[54:57], v[174:177], v[190:193], v[54:57]
	v_mfma_f32_16x16x32_bf16 v[50:53], v[182:185], v[190:193], v[50:53]
	v_mfma_f32_16x16x32_bf16 v[38:41], v[174:177], v[198:201], v[38:41]
	v_mfma_f32_16x16x32_bf16 v[34:37], v[182:185], v[198:201], v[34:37]
	v_mfma_f32_16x16x32_bf16 v[22:25], v[174:177], v[208:211], v[22:25]
	v_mfma_f32_16x16x32_bf16 v[18:21], v[182:185], v[208:211], v[18:21]
	v_mfma_f32_16x16x32_bf16 v[6:9], v[174:177], v[216:219], v[6:9]
	v_mfma_f32_16x16x32_bf16 v[2:5], v[182:185], v[216:219], v[2:5]
	s_setprio 0
	s_barrier
	s_add_i32 s45, s45, 2
	s_add_u32 s69, s69, 0x100
	s_addc_u32 s44, s44, 0
	s_add_u32 s58, s58, 0x100
	s_addc_u32 s59, s59, 0
	s_cmp_gt_u32 s45, 29
	s_cbranch_scc0 .LBB1_87
	s_and_b64 vcc, exec, s[26:27]
	s_cbranch_vccz .LBB1_90
	s_barrier

; #define PG8_STAGE(bufoff, gbase, voff) do { _Pragma("unroll") for (int _i = 0; _i < 2; ++_i) \
;         __builtin_amdgcn_global_load_lds((const unsigned*)((const char*)(gbase) + (voff)[_i]), (LAS unsigned*)(lds + (bufoff) + ldsw + _i * 8192), 16, 0, 0); } while (0)
; #define PG8_LDA(dst, b, h) do { _Pragma("unroll") for (int m = 0; m < 4; ++m) _Pragma("unroll") for (int k = 0; k < 2; ++k) dst[m][k] = *(const LAS bf16x8*)(lds + PG8_SA(b, h) + aoff + m * 2048 + k * 1024); } while (0)
; #define PG8_LDB(dst, b, h) do { _Pragma("unroll") for (int n = 0; n < 2; ++n) _Pragma("unroll") for (int k = 0; k < 2; ++k) dst[n][k] = *(const LAS bf16x8*)(lds + PG8_SB(b, h) + boff + n * 2048 + k * 1024); } while (0)
; #define PG8_WAIT_V(n) asm volatile("s_waitcnt vmcnt(" #n ")" ::: "memory")
; #define PG8_BAR __builtin_amdgcn_s_barrier()
; template <class Epi, class Sched>
; __device__ __forceinline__ void gemm_phase(LAS unsigned char* lds, const Gemm g, const Sched& S, const Epi& E, const int tid) {
;     ...
;         for (int t = 0; t < nt; t += 2) {
;             const bool last = (t == nt - 2);
;             const char* a1 = cA + (size_t)(t + 1) * kstep;
;             const char* a2 = last ? nA : cA + (size_t)(t + 2) * kstep; const char* b2 = last ? nB : cB + (size_t)(t + 2) * kstep;
;             const char* a3 = a2 + kstep; const char* b3 = b2 + kstep;
;             PG8_LDB(B0, 0, 0); PG8_LDB(B1, 0, 1); PG8_SCHED; PG8_LDA(At, 0, 0); PG8_STAGE(PG8_SA(1, 1), a1 + hstepA, voffA);
;             PG8_WAIT_V(8); PG8_WAIT_L(0); PG8_BAR; PG8_MMA(0, 0, At, B0); PG8_MMA(0, 1, At, B1); PG8_BAR; PG8_SCHED;
;             PG8_LDA(At, 0, 1); PG8_STAGE(PG8_SB(0, 0), b2, voffB); PG8_STAGE(PG8_SB(0, 1), b2 + hstepB, voffB); PG8_STAGE(PG8_SA(0, 0), a2, voffA);
;             PG8_WAIT_V(8); PG8_WAIT_L(0); PG8_BAR; PG8_MMA(1, 0, At, B0); PG8_MMA(1, 1, At, B1); PG8_BAR; PG8_SCHED;
;             PG8_LDB(B0, 1, 0); PG8_LDB(B1, 1, 1); PG8_SCHED; PG8_LDA(At, 1, 0); PG8_STAGE(PG8_SA(0, 1), a2 + hstepA, voffA);
;             PG8_WAIT_V(8); PG8_WAIT_L(0); PG8_BAR; PG8_MMA(0, 0, At, B0); PG8_MMA(0, 1, At, B1); PG8_BAR; PG8_SCHED;
;             PG8_LDA(At, 1, 1); PG8_STAGE(PG8_SB(1, 0), b3, voffB); PG8_STAGE(PG8_SB(1, 1), b3 + hstepB, voffB); PG8_STAGE(PG8_SA(1, 0), a3, voffA);
;             PG8_WAIT_V(8); PG8_WAIT_L(0); PG8_BAR; PG8_MMA(1, 0, At, B0); PG8_MMA(1, 1, At, B1); PG8_BAR; PG8_SCHED;
.LBB1_113:
	s_add_u32 s14, s64, 0xfff80080
	s_addc_u32 s15, s65, -1
	s_add_i32 s76, 0, 0x10000
	s_cmp_eq_u32 s45, 28
	s_cselect_b32 s69, s49, s15
	s_cselect_b32 s68, s61, s14
	s_cselect_b32 s67, s53, s44
	s_cselect_b32 s66, s74, s75
	s_add_i32 s77, 0, 0x14000
	v_add_u32_e32 v142, s76, v207
	v_add_u32_e32 v158, s77, v207
	ds_read_b128 v[130:133], v142
	ds_read_b128 v[134:137], v142 offset:1024
	ds_read_b128 v[138:141], v142 offset:2048
	ds_read_b128 v[142:145], v142 offset:3072
	ds_read_b128 v[146:149], v158
	ds_read_b128 v[150:153], v158 offset:1024
	ds_read_b128 v[154:157], v158 offset:2048
	ds_read_b128 v[158:161], v158 offset:3072
	s_add_i32 m0, s47, 0xc000
	ds_read_b128 v[162:165], v212
	ds_read_b128 v[166:169], v212 offset:1024
	ds_read_b128 v[170:173], v212 offset:2048
	ds_read_b128 v[174:177], v212 offset:3072
	ds_read_b128 v[188:191], v212 offset:4096
	ds_read_b128 v[192:195], v212 offset:5120
	ds_read_b128 v[196:199], v212 offset:6144
	ds_read_b128 v[214:217], v212 offset:7168
	global_load_lds_dwordx4 v186, s[64:65]
	s_add_i32 m0, s47, 0xe000
	s_nop 0
	global_load_lds_dwordx4 v184, s[64:65]
	s_waitcnt vmcnt(8)
	s_waitcnt lgkmcnt(0)
	s_barrier
	s_setprio 1
	s_waitcnt lgkmcnt(0)
	v_mfma_f32_16x16x32_bf16 v[126:129], v[130:133], v[162:165], v[126:129]
	v_mfma_f32_16x16x32_bf16 v[122:125], v[138:141], v[162:165], v[122:125]
	v_mfma_f32_16x16x32_bf16 v[110:113], v[130:133], v[170:173], v[110:113]
	v_mfma_f32_16x16x32_bf16 v[106:109], v[138:141], v[170:173], v[106:109]
	v_mfma_f32_16x16x32_bf16 v[94:97], v[130:133], v[188:191], v[94:97]
	v_mfma_f32_16x16x32_bf16 v[90:93], v[138:141], v[188:191], v[90:93]
	v_mfma_f32_16x16x32_bf16 v[78:81], v[130:133], v[196:199], v[78:81]
	v_mfma_f32_16x16x32_bf16 v[74:77], v[138:141], v[196:199], v[74:77]
	v_mfma_f32_16x16x32_bf16 v[126:129], v[134:137], v[166:169], v[126:129]
	v_mfma_f32_16x16x32_bf16 v[122:125], v[142:145], v[166:169], v[122:125]
	v_mfma_f32_16x16x32_bf16 v[110:113], v[134:137], v[174:177], v[110:113]
	v_mfma_f32_16x16x32_bf16 v[106:109], v[142:145], v[174:177], v[106:109]
	v_mfma_f32_16x16x32_bf16 v[94:97], v[134:137], v[192:195], v[94:97]
	v_mfma_f32_16x16x32_bf16 v[90:93], v[142:145], v[192:195], v[90:93]
	v_mfma_f32_16x16x32_bf16 v[78:81], v[134:137], v[214:217], v[78:81]
	v_mfma_f32_16x16x32_bf16 v[74:77], v[142:145], v[214:217], v[74:77]
	s_setprio 0
	s_setprio 1
	v_mfma_f32_16x16x32_bf16 v[118:121], v[146:149], v[162:165], v[118:121]
	v_mfma_f32_16x16x32_bf16 v[114:117], v[154:157], v[162:165], v[114:117]
	v_mfma_f32_16x16x32_bf16 v[102:105], v[146:149], v[170:173], v[102:105]
	v_mfma_f32_16x16x32_bf16 v[98:101], v[154:157], v[170:173], v[98:101]
	v_mfma_f32_16x16x32_bf16 v[86:89], v[146:149], v[188:191], v[86:89]
	v_mfma_f32_16x16x32_bf16 v[82:85], v[154:157], v[188:191], v[82:85]
	v_mfma_f32_16x16x32_bf16 v[70:73], v[146:149], v[196:199], v[70:73]
	v_mfma_f32_16x16x32_bf16 v[66:69], v[154:157], v[196:199], v[66:69]
	v_mfma_f32_16x16x32_bf16 v[118:121], v[150:153], v[166:169], v[118:121]
	v_mfma_f32_16x16x32_bf16 v[114:117], v[158:161], v[166:169], v[114:117]
	v_mfma_f32_16x16x32_bf16 v[102:105], v[150:153], v[174:177], v[102:105]
	v_mfma_f32_16x16x32_bf16 v[98:101], v[158:161], v[174:177], v[98:101]
	v_mfma_f32_16x16x32_bf16 v[86:89], v[150:153], v[192:195], v[86:89]
	v_mfma_f32_16x16x32_bf16 v[82:85], v[158:161], v[192:195], v[82:85]
	v_mfma_f32_16x16x32_bf16 v[70:73], v[150:153], v[214:217], v[70:73]
	v_mfma_f32_16x16x32_bf16 v[66:69], v[158:161], v[214:217], v[66:69]
	s_setprio 0
	s_barrier
	s_add_i32 s14, s76, s46
	s_mov_b32 m0, s14
	ds_read_b128 v[162:165], v212 offset:16384
	ds_read_b128 v[166:169], v212 offset:17408
	ds_read_b128 v[170:173], v212 offset:18432
	ds_read_b128 v[174:177], v212 offset:19456
	ds_read_b128 v[188:191], v212 offset:20480
	ds_read_b128 v[192:195], v212 offset:21504
	ds_read_b128 v[196:199], v212 offset:22528
	ds_read_b128 v[214:217], v212 offset:23552
	global_load_lds_dwordx4 v0, s[66:67]
	s_add_i32 m0, s14, 0x2000
	s_add_u32 s14, s66, 0x80000
	s_addc_u32 s15, s67, 0
	s_add_i32 s76, s77, s46
	global_load_lds_dwordx4 v182, s[66:67]
	s_mov_b32 m0, s76
	s_nop 0
	global_load_lds_dwordx4 v0, s[14:15]
	s_add_i32 m0, s76, 0x2000
	s_nop 0
	global_load_lds_dwordx4 v182, s[14:15]
	s_mov_b32 m0, s47
	s_nop 0
	global_load_lds_dwordx4 v178, s[68:69]
	s_mov_b32 m0, s63
	s_nop 0
	global_load_lds_dwordx4 v180, s[68:69]
	s_waitcnt vmcnt(8)
	s_waitcnt lgkmcnt(0)
	s_barrier
	s_setprio 1
	s_waitcnt lgkmcnt(0)
	v_mfma_f32_16x16x32_bf16 v[62:65], v[130:133], v[162:165], v[62:65]
	v_mfma_f32_16x16x32_bf16 v[58:61], v[138:141], v[162:165], v[58:61]
	v_mfma_f32_16x16x32_bf16 v[46:49], v[130:133], v[170:173], v[46:49]
	v_mfma_f32_16x16x32_bf16 v[42:45], v[138:141], v[170:173], v[42:45]
	v_mfma_f32_16x16x32_bf16 v[30:33], v[130:133], v[188:191], v[30:33]
	v_mfma_f32_16x16x32_bf16 v[26:29], v[138:141], v[188:191], v[26:29]
	v_mfma_f32_16x16x32_bf16 v[14:17], v[130:133], v[196:199], v[14:17]
	v_mfma_f32_16x16x32_bf16 v[10:13], v[138:141], v[196:199], v[10:13]
	v_mfma_f32_16x16x32_bf16 v[62:65], v[134:137], v[166:169], v[62:65]
	v_mfma_f32_16x16x32_bf16 v[58:61], v[142:145], v[166:169], v[58:61]
	v_mfma_f32_16x16x32_bf16 v[46:49], v[134:137], v[174:177], v[46:49]
	v_mfma_f32_16x16x32_bf16 v[42:45], v[142:145], v[174:177], v[42:45]
	v_mfma_f32_16x16x32_bf16 v[30:33], v[134:137], v[192:195], v[30:33]
	v_mfma_f32_16x16x32_bf16 v[26:29], v[142:145], v[192:195], v[26:29]
	v_mfma_f32_16x16x32_bf16 v[14:17], v[134:137], v[214:217], v[14:17]
	v_mfma_f32_16x16x32_bf16 v[10:13], v[142:145], v[214:217], v[10:13]
	s_setprio 0
	s_setprio 1
	v_mfma_f32_16x16x32_bf16 v[54:57], v[146:149], v[162:165], v[54:57]
	v_mfma_f32_16x16x32_bf16 v[50:53], v[154:157], v[162:165], v[50:53]
	v_mfma_f32_16x16x32_bf16 v[38:41], v[146:149], v[170:173], v[38:41]
	v_mfma_f32_16x16x32_bf16 v[34:37], v[154:157], v[170:173], v[34:37]
	v_mfma_f32_16x16x32_bf16 v[22:25], v[146:149], v[188:191], v[22:25]
	v_mfma_f32_16x16x32_bf16 v[18:21], v[154:157], v[188:191], v[18:21]
	v_mfma_f32_16x16x32_bf16 v[6:9], v[146:149], v[196:199], v[6:9]
	v_mfma_f32_16x16x32_bf16 v[2:5], v[154:157], v[196:199], v[2:5]
	v_mfma_f32_16x16x32_bf16 v[54:57], v[150:153], v[166:169], v[54:57]
	v_mfma_f32_16x16x32_bf16 v[50:53], v[158:161], v[166:169], v[50:53]
	v_mfma_f32_16x16x32_bf16 v[38:41], v[150:153], v[174:177], v[38:41]
	v_mfma_f32_16x16x32_bf16 v[34:37], v[158:161], v[174:177], v[34:37]
	v_mfma_f32_16x16x32_bf16 v[22:25], v[150:153], v[192:195], v[22:25]
	v_mfma_f32_16x16x32_bf16 v[18:21], v[158:161], v[192:195], v[18:21]
	v_mfma_f32_16x16x32_bf16 v[6:9], v[150:153], v[214:217], v[6:9]
	v_mfma_f32_16x16x32_bf16 v[2:5], v[158:161], v[214:217], v[2:5]
	s_setprio 0
	s_barrier
; #define PG8_STAGE(bufoff, gbase, voff) do { _Pragma("unroll") for (int _i = 0; _i < 2; ++_i) \
;         __builtin_amdgcn_global_load_lds((const unsigned*)((const char*)(gbase) + (voff)[_i]), (LAS unsigned*)(lds + (bufoff) + ldsw + _i * 8192), 16, 0, 0); } while (0)
; #define PG8_LDA(dst, b, h) do { _Pragma("unroll") for (int m = 0; m < 4; ++m) _Pragma("unroll") for (int k = 0; k < 2; ++k) dst[m][k] = *(const LAS bf16x8*)(lds + PG8_SA(b, h) + aoff + m * 2048 + k * 1024); } while (0)
; #define PG8_LDB(dst, b, h) do { _Pragma("unroll") for (int n = 0; n < 2; ++n) _Pragma("unroll") for (int k = 0; k < 2; ++k) dst[n][k] = *(const LAS bf16x8*)(lds + PG8_SB(b, h) + boff + n * 2048 + k * 1024); } while (0)
; #define PG8_WAIT_V(n) asm volatile("s_waitcnt vmcnt(" #n ")" ::: "memory")
; template <class Epi, class Sched>
; __device__ __forceinline__ void gemm_phase(LAS unsigned char* lds, const Gemm g, const Sched& S, const Epi& E, const int tid) {
;     ...
;         for (int t = 0; t < nt; t += 2) {
;             const bool last = (t == nt - 2);
;             const char* a1 = cA + (size_t)(t + 1) * kstep;
;             const char* a2 = last ? nA : cA + (size_t)(t + 2) * kstep; const char* b2 = last ? nB : cB + (size_t)(t + 2) * kstep;
;             const char* a3 = a2 + kstep; const char* b3 = b2 + kstep;
;             PG8_LDB(B0, 0, 0); PG8_LDB(B1, 0, 1); PG8_SCHED; PG8_LDA(At, 0, 0); PG8_STAGE(PG8_SA(1, 1), a1 + hstepA, voffA);
;             PG8_WAIT_V(8); PG8_WAIT_L(0); PG8_BAR; PG8_MMA(0, 0, At, B0); PG8_MMA(0, 1, At, B1); PG8_BAR; PG8_SCHED;
;             PG8_LDA(At, 0, 1); PG8_STAGE(PG8_SB(0, 0), b2, voffB); PG8_STAGE(PG8_SB(0, 1), b2 + hstepB, voffB); PG8_STAGE(PG8_SA(0, 0), a2, voffA);
;             PG8_WAIT_V(8); PG8_WAIT_L(0); PG8_BAR; PG8_MMA(1, 0, At, B0); PG8_MMA(1, 1, At, B1); PG8_BAR; PG8_SCHED;
;             PG8_LDB(B0, 1, 0); PG8_LDB(B1, 1, 1); PG8_SCHED; PG8_LDA(At, 1, 0); PG8_STAGE(PG8_SA(0, 1), a2 + hstepA, voffA);
;             PG8_WAIT_V(8); PG8_WAIT_L(0); PG8_BAR; PG8_MMA(0, 0, At, B0); PG8_MMA(0, 1, At, B1); PG8_BAR; PG8_SCHED;
;             PG8_LDA(At, 1, 1); PG8_STAGE(PG8_SB(1, 0), b3, voffB); PG8_STAGE(PG8_SB(1, 1), b3 + hstepB, voffB); PG8_STAGE(PG8_SA(1, 0), a3, voffA);
;             PG8_WAIT_V(8); PG8_WAIT_L(0); PG8_BAR; PG8_MMA(1, 0, At, B0); PG8_MMA(1, 1, At, B1); PG8_BAR; PG8_SCHED;
;         }
;         if (wr == 0) PG8_BAR;
	s_add_i32 s76, 0, 0x18000
	s_add_i32 s77, 0, 0x1c000
	v_add_u32_e32 v142, s76, v207
	v_add_u32_e32 v158, s77, v207
	ds_read_b128 v[130:133], v142
	ds_read_b128 v[134:137], v142 offset:1024
	ds_read_b128 v[138:141], v142 offset:2048
	ds_read_b128 v[142:145], v142 offset:3072
	ds_read_b128 v[146:149], v158
	ds_read_b128 v[150:153], v158 offset:1024
	ds_read_b128 v[154:157], v158 offset:2048
	ds_read_b128 v[158:161], v158 offset:3072
	s_add_u32 s14, s68, 0x80000
	s_addc_u32 s15, s69, 0
	s_mov_b32 m0, s84
	ds_read_b128 v[162:165], v212 offset:32768
	ds_read_b128 v[166:169], v212 offset:33792
	ds_read_b128 v[170:173], v212 offset:34816
	ds_read_b128 v[174:177], v212 offset:35840
	ds_read_b128 v[188:191], v212 offset:36864
	ds_read_b128 v[192:195], v212 offset:37888
	ds_read_b128 v[196:199], v212 offset:38912
	ds_read_b128 v[214:217], v212 offset:39936
	global_load_lds_dwordx4 v178, s[14:15]
	s_mov_b32 m0, s85
	s_nop 0
	global_load_lds_dwordx4 v180, s[14:15]
	s_waitcnt vmcnt(8)
	s_waitcnt lgkmcnt(0)
	s_barrier
	s_setprio 1
	s_waitcnt lgkmcnt(0)
	v_mfma_f32_16x16x32_bf16 v[126:129], v[130:133], v[162:165], v[126:129]
	v_mfma_f32_16x16x32_bf16 v[122:125], v[138:141], v[162:165], v[122:125]
	v_mfma_f32_16x16x32_bf16 v[110:113], v[130:133], v[170:173], v[110:113]
	v_mfma_f32_16x16x32_bf16 v[106:109], v[138:141], v[170:173], v[106:109]
	v_mfma_f32_16x16x32_bf16 v[94:97], v[130:133], v[188:191], v[94:97]
	v_mfma_f32_16x16x32_bf16 v[90:93], v[138:141], v[188:191], v[90:93]
	v_mfma_f32_16x16x32_bf16 v[78:81], v[130:133], v[196:199], v[78:81]
	v_mfma_f32_16x16x32_bf16 v[74:77], v[138:141], v[196:199], v[74:77]
	v_mfma_f32_16x16x32_bf16 v[126:129], v[134:137], v[166:169], v[126:129]
	v_mfma_f32_16x16x32_bf16 v[122:125], v[142:145], v[166:169], v[122:125]
	v_mfma_f32_16x16x32_bf16 v[110:113], v[134:137], v[174:177], v[110:113]
	v_mfma_f32_16x16x32_bf16 v[106:109], v[142:145], v[174:177], v[106:109]
	v_mfma_f32_16x16x32_bf16 v[94:97], v[134:137], v[192:195], v[94:97]
	v_mfma_f32_16x16x32_bf16 v[90:93], v[142:145], v[192:195], v[90:93]
	v_mfma_f32_16x16x32_bf16 v[78:81], v[134:137], v[214:217], v[78:81]
	v_mfma_f32_16x16x32_bf16 v[74:77], v[142:145], v[214:217], v[74:77]
	s_setprio 0
	s_setprio 1
	v_mfma_f32_16x16x32_bf16 v[118:121], v[146:149], v[162:165], v[118:121]
	v_mfma_f32_16x16x32_bf16 v[114:117], v[154:157], v[162:165], v[114:117]
	v_mfma_f32_16x16x32_bf16 v[102:105], v[146:149], v[170:173], v[102:105]
	v_mfma_f32_16x16x32_bf16 v[98:101], v[154:157], v[170:173], v[98:101]
	v_mfma_f32_16x16x32_bf16 v[86:89], v[146:149], v[188:191], v[86:89]
	v_mfma_f32_16x16x32_bf16 v[82:85], v[154:157], v[188:191], v[82:85]
	v_mfma_f32_16x16x32_bf16 v[70:73], v[146:149], v[196:199], v[70:73]
	v_mfma_f32_16x16x32_bf16 v[66:69], v[154:157], v[196:199], v[66:69]
	v_mfma_f32_16x16x32_bf16 v[118:121], v[150:153], v[166:169], v[118:121]
	v_mfma_f32_16x16x32_bf16 v[114:117], v[158:161], v[166:169], v[114:117]
	v_mfma_f32_16x16x32_bf16 v[102:105], v[150:153], v[174:177], v[102:105]
	v_mfma_f32_16x16x32_bf16 v[98:101], v[158:161], v[174:177], v[98:101]
	v_mfma_f32_16x16x32_bf16 v[86:89], v[150:153], v[192:195], v[86:89]
	v_mfma_f32_16x16x32_bf16 v[82:85], v[158:161], v[192:195], v[82:85]
	v_mfma_f32_16x16x32_bf16 v[70:73], v[150:153], v[214:217], v[70:73]
	v_mfma_f32_16x16x32_bf16 v[66:69], v[158:161], v[214:217], v[66:69]
	s_setprio 0
	s_barrier
	s_add_i32 s14, s76, s46
	s_add_u32 s100, s66, 0x80
	s_addc_u32 s101, s67, 0
	s_mov_b32 m0, s14
	ds_read_b128 v[162:165], v212 offset:49152
	ds_read_b128 v[166:169], v212 offset:50176
	ds_read_b128 v[170:173], v212 offset:51200
	ds_read_b128 v[174:177], v212 offset:52224
	ds_read_b128 v[188:191], v212 offset:53248
	ds_read_b128 v[192:195], v212 offset:54272
	ds_read_b128 v[196:199], v212 offset:55296
	ds_read_b128 v[214:217], v212 offset:56320
	global_load_lds_dwordx4 v0, s[100:101]
	s_add_i32 m0, s14, 0x2000
	s_add_u32 s14, s66, 0x80080
	s_addc_u32 s15, s67, 0
	s_add_i32 s66, s77, s46
	global_load_lds_dwordx4 v182, s[100:101]
	s_mov_b32 m0, s66
	s_nop 0
	global_load_lds_dwordx4 v0, s[14:15]
	s_add_i32 m0, s66, 0x2000
	s_nop 0
	global_load_lds_dwordx4 v182, s[14:15]
	s_add_u32 s100, s68, 0x80
	s_addc_u32 s101, s69, 0
	s_mov_b32 m0, s72
	s_nop 0
	global_load_lds_dwordx4 v178, s[100:101]
	s_mov_b32 m0, s73
	s_nop 0
	global_load_lds_dwordx4 v180, s[100:101]
	s_waitcnt vmcnt(8)
	s_waitcnt lgkmcnt(0)
	s_barrier
	s_setprio 1
	s_waitcnt lgkmcnt(0)
	v_mfma_f32_16x16x32_bf16 v[62:65], v[130:133], v[162:165], v[62:65]
	v_mfma_f32_16x16x32_bf16 v[58:61], v[138:141], v[162:165], v[58:61]
	v_mfma_f32_16x16x32_bf16 v[46:49], v[130:133], v[170:173], v[46:49]
	v_mfma_f32_16x16x32_bf16 v[42:45], v[138:141], v[170:173], v[42:45]
	v_mfma_f32_16x16x32_bf16 v[30:33], v[130:133], v[188:191], v[30:33]
	v_mfma_f32_16x16x32_bf16 v[26:29], v[138:141], v[188:191], v[26:29]
	v_mfma_f32_16x16x32_bf16 v[14:17], v[130:133], v[196:199], v[14:17]
	v_mfma_f32_16x16x32_bf16 v[10:13], v[138:141], v[196:199], v[10:13]
	v_mfma_f32_16x16x32_bf16 v[62:65], v[134:137], v[166:169], v[62:65]
	v_mfma_f32_16x16x32_bf16 v[58:61], v[142:145], v[166:169], v[58:61]
	v_mfma_f32_16x16x32_bf16 v[46:49], v[134:137], v[174:177], v[46:49]
	v_mfma_f32_16x16x32_bf16 v[42:45], v[142:145], v[174:177], v[42:45]
	v_mfma_f32_16x16x32_bf16 v[30:33], v[134:137], v[192:195], v[30:33]
	v_mfma_f32_16x16x32_bf16 v[26:29], v[142:145], v[192:195], v[26:29]
	v_mfma_f32_16x16x32_bf16 v[14:17], v[134:137], v[214:217], v[14:17]
	v_mfma_f32_16x16x32_bf16 v[10:13], v[142:145], v[214:217], v[10:13]
	s_setprio 0
	s_setprio 1
	v_mfma_f32_16x16x32_bf16 v[54:57], v[146:149], v[162:165], v[54:57]
	v_mfma_f32_16x16x32_bf16 v[50:53], v[154:157], v[162:165], v[50:53]
	v_mfma_f32_16x16x32_bf16 v[38:41], v[146:149], v[170:173], v[38:41]
	v_mfma_f32_16x16x32_bf16 v[34:37], v[154:157], v[170:173], v[34:37]
	v_mfma_f32_16x16x32_bf16 v[22:25], v[146:149], v[188:191], v[22:25]
	v_mfma_f32_16x16x32_bf16 v[18:21], v[154:157], v[188:191], v[18:21]
	v_mfma_f32_16x16x32_bf16 v[6:9], v[146:149], v[196:199], v[6:9]
	v_mfma_f32_16x16x32_bf16 v[2:5], v[154:157], v[196:199], v[2:5]
	v_mfma_f32_16x16x32_bf16 v[54:57], v[150:153], v[166:169], v[54:57]
	v_mfma_f32_16x16x32_bf16 v[50:53], v[158:161], v[166:169], v[50:53]
	v_mfma_f32_16x16x32_bf16 v[38:41], v[150:153], v[174:177], v[38:41]
	v_mfma_f32_16x16x32_bf16 v[34:37], v[158:161], v[174:177], v[34:37]
	v_mfma_f32_16x16x32_bf16 v[22:25], v[150:153], v[192:195], v[22:25]
	v_mfma_f32_16x16x32_bf16 v[18:21], v[158:161], v[192:195], v[18:21]
	v_mfma_f32_16x16x32_bf16 v[6:9], v[150:153], v[214:217], v[6:9]
	v_mfma_f32_16x16x32_bf16 v[2:5], v[158:161], v[214:217], v[2:5]
	s_setprio 0
	s_barrier
	s_add_i32 s45, s45, 2
	s_add_u32 s75, s75, 0x100
	s_addc_u32 s44, s44, 0
	s_add_u32 s64, s64, 0x100
	s_addc_u32 s65, s65, 0
	s_cmp_gt_u32 s45, 29
	s_cbranch_scc0 .LBB1_113
	s_and_b64 vcc, exec, s[42:43]
	s_cbranch_vccz .LBB1_116
	s_barrier

; #define PG8_STAGE(bufoff, gbase, voff) do { _Pragma("unroll") for (int _i = 0; _i < 2; ++_i) \
;         __builtin_amdgcn_global_load_lds((const unsigned*)((const char*)(gbase) + (voff)[_i]), (LAS unsigned*)(lds + (bufoff) + ldsw + _i * 8192), 16, 0, 0); } while (0)
; #define PG8_LDA(dst, b, h) do { _Pragma("unroll") for (int m = 0; m < 4; ++m) _Pragma("unroll") for (int k = 0; k < 2; ++k) dst[m][k] = *(const LAS bf16x8*)(lds + PG8_SA(b, h) + aoff + m * 2048 + k * 1024); } while (0)
; #define PG8_LDB(dst, b, h) do { _Pragma("unroll") for (int n = 0; n < 2; ++n) _Pragma("unroll") for (int k = 0; k < 2; ++k) dst[n][k] = *(const LAS bf16x8*)(lds + PG8_SB(b, h) + boff + n * 2048 + k * 1024); } while (0)
; #define PG8_MMA(ai, bj, At, Bt) do { __builtin_amdgcn_s_setprio(1); _Pragma("unroll") for (int m = 0; m < 4; ++m) _Pragma("unroll") for (int n = 0; n < 2; ++n) _Pragma("unroll") for (int k = 0; k < 2; ++k) \
;         acc[ai][bj][m][n] = __builtin_amdgcn_mfma_f32_16x16x32_bf16(Bt[n][k], At[m][k], acc[ai][bj][m][n], 0, 0, 0); __builtin_amdgcn_s_setprio(0); } while (0)
; #define PG8_WAIT_V(n) asm volatile("s_waitcnt vmcnt(" #n ")" ::: "memory")
; #define PG8_WAIT_L(n) asm volatile("s_waitcnt lgkmcnt(" #n ")" ::: "memory")
; #define PG8_BAR __builtin_amdgcn_s_barrier()
; #define PG8_SCHED __builtin_amdgcn_sched_barrier(0)
; template <class Epi, class Sched>
; __device__ __forceinline__ void gemm_phase(LAS unsigned char* lds, const Gemm g, const Sched& S, const Epi& E, const int tid) {
;     ...
;             const char* a1 = cA + (size_t)(t + 1) * kstep;
;             const char* a2 = last ? nA : cA + (size_t)(t + 2) * kstep; const char* b2 = last ? nB : cB + (size_t)(t + 2) * kstep;
;             const char* a3 = a2 + kstep; const char* b3 = b2 + kstep;
;             PG8_LDB(B0, 0, 0); PG8_LDB(B1, 0, 1); PG8_SCHED; PG8_LDA(At, 0, 0); PG8_STAGE(PG8_SA(1, 1), a1 + hstepA, voffA);
;             PG8_WAIT_V(8); PG8_WAIT_L(0); PG8_BAR; PG8_MMA(0, 0, At, B0); PG8_MMA(0, 1, At, B1); PG8_BAR; PG8_SCHED;
;             PG8_LDA(At, 0, 1); PG8_STAGE(PG8_SB(0, 0), b2, voffB); PG8_STAGE(PG8_SB(0, 1), b2 + hstepB, voffB); PG8_STAGE(PG8_SA(0, 0), a2, voffA);
;             PG8_WAIT_V(8); PG8_WAIT_L(0); PG8_BAR; PG8_MMA(1, 0, At, B0); PG8_MMA(1, 1, At, B1); PG8_BAR; PG8_SCHED;
.LBB1_156:
	s_add_u32 s40, s60, 0x100
	s_addc_u32 s41, s61, 0
	s_add_i32 s49, 0, 0x10000
	s_cmp_eq_u32 s45, 12
	s_cselect_b32 s65, s57, s41
	s_cselect_b32 s64, s56, s40
	s_cselect_b32 s63, s14, s44
	s_cselect_b32 s62, s15, s43
	s_add_i32 s53, 0, 0x14000
	v_add_u32_e32 v142, s49, v231
	v_add_u32_e32 v158, s53, v231
	ds_read_b128 v[130:133], v142
	ds_read_b128 v[134:137], v142 offset:1024
	ds_read_b128 v[138:141], v142 offset:2048
	ds_read_b128 v[142:145], v142 offset:3072
	ds_read_b128 v[146:149], v158
	ds_read_b128 v[150:153], v158 offset:1024
	ds_read_b128 v[154:157], v158 offset:2048
	ds_read_b128 v[158:161], v158 offset:3072
	s_add_i32 m0, s47, 0xc000
	ds_read_b128 v[162:165], v236
	ds_read_b128 v[166:169], v236 offset:1024
	ds_read_b128 v[170:173], v236 offset:2048
	ds_read_b128 v[174:177], v236 offset:3072
	ds_read_b128 v[178:181], v236 offset:4096
	ds_read_b128 v[182:185], v236 offset:5120
	ds_read_b128 v[186:189], v236 offset:6144
	ds_read_b128 v[190:193], v236 offset:7168
	global_load_lds_dwordx4 v214, s[60:61]
	s_add_i32 m0, s47, 0xe000
	s_nop 0
	global_load_lds_dwordx4 v212, s[60:61]
	s_waitcnt vmcnt(8)
	s_waitcnt lgkmcnt(0)
	s_barrier
	s_setprio 1
	s_waitcnt lgkmcnt(0)
	v_mfma_f32_16x16x32_bf16 v[126:129], v[130:133], v[162:165], v[126:129]
	v_mfma_f32_16x16x32_bf16 v[122:125], v[138:141], v[162:165], v[122:125]
	v_mfma_f32_16x16x32_bf16 v[118:121], v[130:133], v[170:173], v[118:121]
	v_mfma_f32_16x16x32_bf16 v[114:117], v[138:141], v[170:173], v[114:117]
	v_mfma_f32_16x16x32_bf16 v[110:113], v[130:133], v[178:181], v[110:113]
	v_mfma_f32_16x16x32_bf16 v[106:109], v[138:141], v[178:181], v[106:109]
	v_mfma_f32_16x16x32_bf16 v[102:105], v[130:133], v[186:189], v[102:105]
	v_mfma_f32_16x16x32_bf16 v[98:101], v[138:141], v[186:189], v[98:101]
	v_mfma_f32_16x16x32_bf16 v[126:129], v[134:137], v[166:169], v[126:129]
	v_mfma_f32_16x16x32_bf16 v[122:125], v[142:145], v[166:169], v[122:125]
	v_mfma_f32_16x16x32_bf16 v[118:121], v[134:137], v[174:177], v[118:121]
	v_mfma_f32_16x16x32_bf16 v[114:117], v[142:145], v[174:177], v[114:117]
	v_mfma_f32_16x16x32_bf16 v[110:113], v[134:137], v[182:185], v[110:113]
	v_mfma_f32_16x16x32_bf16 v[106:109], v[142:145], v[182:185], v[106:109]
	v_mfma_f32_16x16x32_bf16 v[102:105], v[134:137], v[190:193], v[102:105]
	v_mfma_f32_16x16x32_bf16 v[98:101], v[142:145], v[190:193], v[98:101]
	s_setprio 0
	s_setprio 1
	v_mfma_f32_16x16x32_bf16 v[94:97], v[146:149], v[162:165], v[94:97]
	v_mfma_f32_16x16x32_bf16 v[90:93], v[154:157], v[162:165], v[90:93]
	v_mfma_f32_16x16x32_bf16 v[86:89], v[146:149], v[170:173], v[86:89]
	v_mfma_f32_16x16x32_bf16 v[82:85], v[154:157], v[170:173], v[82:85]
	v_mfma_f32_16x16x32_bf16 v[78:81], v[146:149], v[178:181], v[78:81]
	v_mfma_f32_16x16x32_bf16 v[74:77], v[154:157], v[178:181], v[74:77]
	v_mfma_f32_16x16x32_bf16 v[70:73], v[146:149], v[186:189], v[70:73]
	v_mfma_f32_16x16x32_bf16 v[66:69], v[154:157], v[186:189], v[66:69]
	v_mfma_f32_16x16x32_bf16 v[94:97], v[150:153], v[166:169], v[94:97]
	v_mfma_f32_16x16x32_bf16 v[90:93], v[158:161], v[166:169], v[90:93]
	v_mfma_f32_16x16x32_bf16 v[86:89], v[150:153], v[174:177], v[86:89]
	v_mfma_f32_16x16x32_bf16 v[82:85], v[158:161], v[174:177], v[82:85]
	v_mfma_f32_16x16x32_bf16 v[78:81], v[150:153], v[182:185], v[78:81]
	v_mfma_f32_16x16x32_bf16 v[74:77], v[158:161], v[182:185], v[74:77]
	v_mfma_f32_16x16x32_bf16 v[70:73], v[150:153], v[190:193], v[70:73]
	v_mfma_f32_16x16x32_bf16 v[66:69], v[158:161], v[190:193], v[66:69]
	s_setprio 0
	s_barrier
	s_add_i32 s49, s49, s46
	s_mov_b32 m0, s49
	ds_read_b128 v[162:165], v236 offset:16384
	ds_read_b128 v[166:169], v236 offset:17408
	ds_read_b128 v[170:173], v236 offset:18432
	ds_read_b128 v[174:177], v236 offset:19456
	ds_read_b128 v[178:181], v236 offset:20480
	ds_read_b128 v[182:185], v236 offset:21504
	ds_read_b128 v[186:189], v236 offset:22528
	ds_read_b128 v[190:193], v236 offset:23552
	global_load_lds_dwordx4 v206, s[62:63]
	s_add_i32 m0, s49, 0x2000
	s_add_u32 s60, s62, 0x40000
	s_addc_u32 s61, s63, 0
	s_add_i32 s49, s53, s46
	global_load_lds_dwordx4 v210, s[62:63]
	s_mov_b32 m0, s49
	s_nop 0
	global_load_lds_dwordx4 v206, s[60:61]
	s_add_i32 m0, s49, 0x2000
	s_nop 0
	global_load_lds_dwordx4 v210, s[60:61]
	s_mov_b32 m0, s47
	s_nop 0
	global_load_lds_dwordx4 v204, s[64:65]
	s_mov_b32 m0, s66
	s_nop 0
	global_load_lds_dwordx4 v208, s[64:65]
	s_waitcnt vmcnt(8)
	s_waitcnt lgkmcnt(0)
	s_barrier
	s_setprio 1
	s_waitcnt lgkmcnt(0)
	v_mfma_f32_16x16x32_bf16 v[62:65], v[130:133], v[162:165], v[62:65]
	v_mfma_f32_16x16x32_bf16 v[58:61], v[138:141], v[162:165], v[58:61]
	v_mfma_f32_16x16x32_bf16 v[54:57], v[130:133], v[170:173], v[54:57]
	v_mfma_f32_16x16x32_bf16 v[50:53], v[138:141], v[170:173], v[50:53]
	v_mfma_f32_16x16x32_bf16 v[46:49], v[130:133], v[178:181], v[46:49]
	v_mfma_f32_16x16x32_bf16 v[42:45], v[138:141], v[178:181], v[42:45]
	v_mfma_f32_16x16x32_bf16 v[38:41], v[130:133], v[186:189], v[38:41]
	v_mfma_f32_16x16x32_bf16 v[34:37], v[138:141], v[186:189], v[34:37]
	v_mfma_f32_16x16x32_bf16 v[62:65], v[134:137], v[166:169], v[62:65]
	v_mfma_f32_16x16x32_bf16 v[58:61], v[142:145], v[166:169], v[58:61]
	v_mfma_f32_16x16x32_bf16 v[54:57], v[134:137], v[174:177], v[54:57]
	v_mfma_f32_16x16x32_bf16 v[50:53], v[142:145], v[174:177], v[50:53]
	v_mfma_f32_16x16x32_bf16 v[46:49], v[134:137], v[182:185], v[46:49]
	v_mfma_f32_16x16x32_bf16 v[42:45], v[142:145], v[182:185], v[42:45]
	v_mfma_f32_16x16x32_bf16 v[38:41], v[134:137], v[190:193], v[38:41]
	v_mfma_f32_16x16x32_bf16 v[34:37], v[142:145], v[190:193], v[34:37]
	s_setprio 0
	s_setprio 1
	v_mfma_f32_16x16x32_bf16 v[30:33], v[146:149], v[162:165], v[30:33]
	v_mfma_f32_16x16x32_bf16 v[26:29], v[154:157], v[162:165], v[26:29]
	v_mfma_f32_16x16x32_bf16 v[22:25], v[146:149], v[170:173], v[22:25]
	v_mfma_f32_16x16x32_bf16 v[18:21], v[154:157], v[170:173], v[18:21]
	v_mfma_f32_16x16x32_bf16 v[14:17], v[146:149], v[178:181], v[14:17]
	v_mfma_f32_16x16x32_bf16 v[10:13], v[154:157], v[178:181], v[10:13]
	v_mfma_f32_16x16x32_bf16 v[6:9], v[146:149], v[186:189], v[6:9]
	v_mfma_f32_16x16x32_bf16 v[2:5], v[154:157], v[186:189], v[2:5]
	v_mfma_f32_16x16x32_bf16 v[30:33], v[150:153], v[166:169], v[30:33]
	v_mfma_f32_16x16x32_bf16 v[26:29], v[158:161], v[166:169], v[26:29]
	v_mfma_f32_16x16x32_bf16 v[22:25], v[150:153], v[174:177], v[22:25]
	v_mfma_f32_16x16x32_bf16 v[18:21], v[158:161], v[174:177], v[18:21]
	v_mfma_f32_16x16x32_bf16 v[14:17], v[150:153], v[182:185], v[14:17]
	v_mfma_f32_16x16x32_bf16 v[10:13], v[158:161], v[182:185], v[10:13]
	v_mfma_f32_16x16x32_bf16 v[6:9], v[150:153], v[190:193], v[6:9]
	v_mfma_f32_16x16x32_bf16 v[2:5], v[158:161], v[190:193], v[2:5]
	s_setprio 0
	s_barrier
; #define PG8_STAGE(bufoff, gbase, voff) do { _Pragma("unroll") for (int _i = 0; _i < 2; ++_i) \
;         __builtin_amdgcn_global_load_lds((const unsigned*)((const char*)(gbase) + (voff)[_i]), (LAS unsigned*)(lds + (bufoff) + ldsw + _i * 8192), 16, 0, 0); } while (0)
; #define PG8_LDA(dst, b, h) do { _Pragma("unroll") for (int m = 0; m < 4; ++m) _Pragma("unroll") for (int k = 0; k < 2; ++k) dst[m][k] = *(const LAS bf16x8*)(lds + PG8_SA(b, h) + aoff + m * 2048 + k * 1024); } while (0)
; #define PG8_LDB(dst, b, h) do { _Pragma("unroll") for (int n = 0; n < 2; ++n) _Pragma("unroll") for (int k = 0; k < 2; ++k) dst[n][k] = *(const LAS bf16x8*)(lds + PG8_SB(b, h) + boff + n * 2048 + k * 1024); } while (0)
; #define PG8_MMA(ai, bj, At, Bt) do { __builtin_amdgcn_s_setprio(1); _Pragma("unroll") for (int m = 0; m < 4; ++m) _Pragma("unroll") for (int n = 0; n < 2; ++n) _Pragma("unroll") for (int k = 0; k < 2; ++k) \
;         acc[ai][bj][m][n] = __builtin_amdgcn_mfma_f32_16x16x32_bf16(Bt[n][k], At[m][k], acc[ai][bj][m][n], 0, 0, 0); __builtin_amdgcn_s_setprio(0); } while (0)
; #define PG8_WAIT_V(n) asm volatile("s_waitcnt vmcnt(" #n ")" ::: "memory")
; #define PG8_WAIT_L(n) asm volatile("s_waitcnt lgkmcnt(" #n ")" ::: "memory")
; #define PG8_BAR __builtin_amdgcn_s_barrier()
; #define PG8_SCHED __builtin_amdgcn_sched_barrier(0)
; template <class Epi, class Sched>
; __device__ __forceinline__ void gemm_phase(LAS unsigned char* lds, const Gemm g, const Sched& S, const Epi& E, const int tid) {
;     ...
;             PG8_LDB(B0, 1, 0); PG8_LDB(B1, 1, 1); PG8_SCHED; PG8_LDA(At, 1, 0); PG8_STAGE(PG8_SA(0, 1), a2 + hstepA, voffA);
;             PG8_WAIT_V(8); PG8_WAIT_L(0); PG8_BAR; PG8_MMA(0, 0, At, B0); PG8_MMA(0, 1, At, B1); PG8_BAR; PG8_SCHED;
;             PG8_LDA(At, 1, 1); PG8_STAGE(PG8_SB(1, 0), b3, voffB); PG8_STAGE(PG8_SB(1, 1), b3 + hstepB, voffB); PG8_STAGE(PG8_SA(1, 0), a3, voffA);
;             PG8_WAIT_V(8); PG8_WAIT_L(0); PG8_BAR; PG8_MMA(1, 0, At, B0); PG8_MMA(1, 1, At, B1); PG8_BAR; PG8_SCHED;
;         }
	s_add_i32 s49, 0, 0x18000
	s_add_i32 s53, 0, 0x1c000
	v_add_u32_e32 v142, s49, v231
	v_add_u32_e32 v158, s53, v231
	ds_read_b128 v[130:133], v142
	ds_read_b128 v[134:137], v142 offset:1024
	ds_read_b128 v[138:141], v142 offset:2048
	ds_read_b128 v[142:145], v142 offset:3072
	ds_read_b128 v[146:149], v158
	ds_read_b128 v[150:153], v158 offset:1024
	ds_read_b128 v[154:157], v158 offset:2048
	ds_read_b128 v[158:161], v158 offset:3072
	s_add_u32 s60, s64, 0x300000
	s_addc_u32 s61, s65, 0
	s_mov_b32 m0, s67
	ds_read_b128 v[162:165], v236 offset:32768
	ds_read_b128 v[166:169], v236 offset:33792
	ds_read_b128 v[170:173], v236 offset:34816
	ds_read_b128 v[174:177], v236 offset:35840
	ds_read_b128 v[178:181], v236 offset:36864
	ds_read_b128 v[182:185], v236 offset:37888
	ds_read_b128 v[186:189], v236 offset:38912
	ds_read_b128 v[190:193], v236 offset:39936
	global_load_lds_dwordx4 v204, s[60:61]
	s_mov_b32 m0, s68
	s_nop 0
	global_load_lds_dwordx4 v208, s[60:61]
	s_waitcnt vmcnt(8)
	s_waitcnt lgkmcnt(0)
	s_barrier
	s_setprio 1
	s_waitcnt lgkmcnt(0)
	v_mfma_f32_16x16x32_bf16 v[126:129], v[130:133], v[162:165], v[126:129]
	v_mfma_f32_16x16x32_bf16 v[122:125], v[138:141], v[162:165], v[122:125]
	v_mfma_f32_16x16x32_bf16 v[118:121], v[130:133], v[170:173], v[118:121]
	v_mfma_f32_16x16x32_bf16 v[114:117], v[138:141], v[170:173], v[114:117]
	v_mfma_f32_16x16x32_bf16 v[110:113], v[130:133], v[178:181], v[110:113]
	v_mfma_f32_16x16x32_bf16 v[106:109], v[138:141], v[178:181], v[106:109]
	v_mfma_f32_16x16x32_bf16 v[102:105], v[130:133], v[186:189], v[102:105]
	v_mfma_f32_16x16x32_bf16 v[98:101], v[138:141], v[186:189], v[98:101]
	v_mfma_f32_16x16x32_bf16 v[126:129], v[134:137], v[166:169], v[126:129]
	v_mfma_f32_16x16x32_bf16 v[122:125], v[142:145], v[166:169], v[122:125]
	v_mfma_f32_16x16x32_bf16 v[118:121], v[134:137], v[174:177], v[118:121]
	v_mfma_f32_16x16x32_bf16 v[114:117], v[142:145], v[174:177], v[114:117]
	v_mfma_f32_16x16x32_bf16 v[110:113], v[134:137], v[182:185], v[110:113]
	v_mfma_f32_16x16x32_bf16 v[106:109], v[142:145], v[182:185], v[106:109]
	v_mfma_f32_16x16x32_bf16 v[102:105], v[134:137], v[190:193], v[102:105]
	v_mfma_f32_16x16x32_bf16 v[98:101], v[142:145], v[190:193], v[98:101]
	s_setprio 0
	s_setprio 1
	v_mfma_f32_16x16x32_bf16 v[94:97], v[146:149], v[162:165], v[94:97]
	v_mfma_f32_16x16x32_bf16 v[90:93], v[154:157], v[162:165], v[90:93]
	v_mfma_f32_16x16x32_bf16 v[86:89], v[146:149], v[170:173], v[86:89]
	v_mfma_f32_16x16x32_bf16 v[82:85], v[154:157], v[170:173], v[82:85]
	v_mfma_f32_16x16x32_bf16 v[78:81], v[146:149], v[178:181], v[78:81]
	v_mfma_f32_16x16x32_bf16 v[74:77], v[154:157], v[178:181], v[74:77]
	v_mfma_f32_16x16x32_bf16 v[70:73], v[146:149], v[186:189], v[70:73]
	v_mfma_f32_16x16x32_bf16 v[66:69], v[154:157], v[186:189], v[66:69]
	v_mfma_f32_16x16x32_bf16 v[94:97], v[150:153], v[166:169], v[94:97]
	v_mfma_f32_16x16x32_bf16 v[90:93], v[158:161], v[166:169], v[90:93]
	v_mfma_f32_16x16x32_bf16 v[86:89], v[150:153], v[174:177], v[86:89]
	v_mfma_f32_16x16x32_bf16 v[82:85], v[158:161], v[174:177], v[82:85]
	v_mfma_f32_16x16x32_bf16 v[78:81], v[150:153], v[182:185], v[78:81]
	v_mfma_f32_16x16x32_bf16 v[74:77], v[158:161], v[182:185], v[74:77]
	v_mfma_f32_16x16x32_bf16 v[70:73], v[150:153], v[190:193], v[70:73]
	v_mfma_f32_16x16x32_bf16 v[66:69], v[158:161], v[190:193], v[66:69]
	s_setprio 0
	s_barrier
	s_add_i32 s49, s49, s46
	s_add_u32 s100, s62, 0x80
	s_addc_u32 s101, s63, 0
	s_mov_b32 m0, s49
	ds_read_b128 v[162:165], v236 offset:49152
	ds_read_b128 v[166:169], v236 offset:50176
	ds_read_b128 v[170:173], v236 offset:51200
	ds_read_b128 v[174:177], v236 offset:52224
	ds_read_b128 v[178:181], v236 offset:53248
	ds_read_b128 v[182:185], v236 offset:54272
	ds_read_b128 v[186:189], v236 offset:55296
	ds_read_b128 v[190:193], v236 offset:56320
	global_load_lds_dwordx4 v206, s[100:101]
	s_add_i32 m0, s49, 0x2000
	s_add_u32 s60, s62, 0x40080
	s_addc_u32 s61, s63, 0
	s_add_i32 s49, s53, s46
	global_load_lds_dwordx4 v210, s[100:101]
	s_mov_b32 m0, s49
	s_nop 0
	global_load_lds_dwordx4 v206, s[60:61]
	s_add_i32 m0, s49, 0x2000
	s_nop 0
	global_load_lds_dwordx4 v210, s[60:61]
	s_add_u32 s100, s64, 0x80
	s_addc_u32 s101, s65, 0
	s_mov_b32 m0, s69
	s_nop 0
	global_load_lds_dwordx4 v204, s[100:101]
	s_mov_b32 m0, s70
	s_nop 0
	global_load_lds_dwordx4 v208, s[100:101]
	s_waitcnt vmcnt(8)
	s_waitcnt lgkmcnt(0)
	s_barrier
	s_setprio 1
	s_waitcnt lgkmcnt(0)
	v_mfma_f32_16x16x32_bf16 v[62:65], v[130:133], v[162:165], v[62:65]
	v_mfma_f32_16x16x32_bf16 v[58:61], v[138:141], v[162:165], v[58:61]
	v_mfma_f32_16x16x32_bf16 v[54:57], v[130:133], v[170:173], v[54:57]
	v_mfma_f32_16x16x32_bf16 v[50:53], v[138:141], v[170:173], v[50:53]
	v_mfma_f32_16x16x32_bf16 v[46:49], v[130:133], v[178:181], v[46:49]
	v_mfma_f32_16x16x32_bf16 v[42:45], v[138:141], v[178:181], v[42:45]
	v_mfma_f32_16x16x32_bf16 v[38:41], v[130:133], v[186:189], v[38:41]
	v_mfma_f32_16x16x32_bf16 v[34:37], v[138:141], v[186:189], v[34:37]
	v_mfma_f32_16x16x32_bf16 v[62:65], v[134:137], v[166:169], v[62:65]
	v_mfma_f32_16x16x32_bf16 v[58:61], v[142:145], v[166:169], v[58:61]
	v_mfma_f32_16x16x32_bf16 v[54:57], v[134:137], v[174:177], v[54:57]
	v_mfma_f32_16x16x32_bf16 v[50:53], v[142:145], v[174:177], v[50:53]
	v_mfma_f32_16x16x32_bf16 v[46:49], v[134:137], v[182:185], v[46:49]
	v_mfma_f32_16x16x32_bf16 v[42:45], v[142:145], v[182:185], v[42:45]
	v_mfma_f32_16x16x32_bf16 v[38:41], v[134:137], v[190:193], v[38:41]
	v_mfma_f32_16x16x32_bf16 v[34:37], v[142:145], v[190:193], v[34:37]
	s_setprio 0
	s_setprio 1
	v_mfma_f32_16x16x32_bf16 v[30:33], v[146:149], v[162:165], v[30:33]
	v_mfma_f32_16x16x32_bf16 v[26:29], v[154:157], v[162:165], v[26:29]
	v_mfma_f32_16x16x32_bf16 v[22:25], v[146:149], v[170:173], v[22:25]
	v_mfma_f32_16x16x32_bf16 v[18:21], v[154:157], v[170:173], v[18:21]
	v_mfma_f32_16x16x32_bf16 v[14:17], v[146:149], v[178:181], v[14:17]
	v_mfma_f32_16x16x32_bf16 v[10:13], v[154:157], v[178:181], v[10:13]
	v_mfma_f32_16x16x32_bf16 v[6:9], v[146:149], v[186:189], v[6:9]
	v_mfma_f32_16x16x32_bf16 v[2:5], v[154:157], v[186:189], v[2:5]
	v_mfma_f32_16x16x32_bf16 v[30:33], v[150:153], v[166:169], v[30:33]
	v_mfma_f32_16x16x32_bf16 v[26:29], v[158:161], v[166:169], v[26:29]
	v_mfma_f32_16x16x32_bf16 v[22:25], v[150:153], v[174:177], v[22:25]
	v_mfma_f32_16x16x32_bf16 v[18:21], v[158:161], v[174:177], v[18:21]
	v_mfma_f32_16x16x32_bf16 v[14:17], v[150:153], v[182:185], v[14:17]
	v_mfma_f32_16x16x32_bf16 v[10:13], v[158:161], v[182:185], v[10:13]
	v_mfma_f32_16x16x32_bf16 v[6:9], v[150:153], v[190:193], v[6:9]
	v_mfma_f32_16x16x32_bf16 v[2:5], v[158:161], v[190:193], v[2:5]
	s_setprio 0
	s_barrier
	s_add_i32 s45, s45, 2
	s_add_u32 s43, s43, 0x100
	s_addc_u32 s44, s44, 0
	s_cmp_gt_u32 s45, 13
	s_mov_b64 s[60:61], s[40:41]
	s_cbranch_scc0 .LBB1_156
	s_and_b64 vcc, exec, s[26:27]
	s_cbranch_vccz .LBB1_159
	s_barrier

; #define PG8_STAGE(bufoff, gbase, voff) do { _Pragma("unroll") for (int _i = 0; _i < 2; ++_i) \
;         __builtin_amdgcn_global_load_lds((const unsigned*)((const char*)(gbase) + (voff)[_i]), (LAS unsigned*)(lds + (bufoff) + ldsw + _i * 8192), 16, 0, 0); } while (0)
; #define PG8_LDA(dst, b, h) do { _Pragma("unroll") for (int m = 0; m < 4; ++m) _Pragma("unroll") for (int k = 0; k < 2; ++k) dst[m][k] = *(const LAS bf16x8*)(lds + PG8_SA(b, h) + aoff + m * 2048 + k * 1024); } while (0)
; #define PG8_LDB(dst, b, h) do { _Pragma("unroll") for (int n = 0; n < 2; ++n) _Pragma("unroll") for (int k = 0; k < 2; ++k) dst[n][k] = *(const LAS bf16x8*)(lds + PG8_SB(b, h) + boff + n * 2048 + k * 1024); } while (0)
; #define PG8_MMA(ai, bj, At, Bt) do { __builtin_amdgcn_s_setprio(1); _Pragma("unroll") for (int m = 0; m < 4; ++m) _Pragma("unroll") for (int n = 0; n < 2; ++n) _Pragma("unroll") for (int k = 0; k < 2; ++k) \
;         acc[ai][bj][m][n] = __builtin_amdgcn_mfma_f32_16x16x32_bf16(Bt[n][k], At[m][k], acc[ai][bj][m][n], 0, 0, 0); __builtin_amdgcn_s_setprio(0); } while (0)
; #define PG8_WAIT_V(n) asm volatile("s_waitcnt vmcnt(" #n ")" ::: "memory")
; #define PG8_WAIT_L(n) asm volatile("s_waitcnt lgkmcnt(" #n ")" ::: "memory")
; #define PG8_BAR __builtin_amdgcn_s_barrier()
; #define PG8_SCHED __builtin_amdgcn_sched_barrier(0)
; template <class Epi, class Sched>
; __device__ __forceinline__ void gemm_phase(LAS unsigned char* lds, const Gemm g, const Sched& S, const Epi& E, const int tid) {
;     ...
;             const char* a1 = cA + (size_t)(t + 1) * kstep;
;             const char* a2 = last ? nA : cA + (size_t)(t + 2) * kstep; const char* b2 = last ? nB : cB + (size_t)(t + 2) * kstep;
;             const char* a3 = a2 + kstep; const char* b3 = b2 + kstep;
;             PG8_LDB(B0, 0, 0); PG8_LDB(B1, 0, 1); PG8_SCHED; PG8_LDA(At, 0, 0); PG8_STAGE(PG8_SA(1, 1), a1 + hstepA, voffA);
;             PG8_WAIT_V(8); PG8_WAIT_L(0); PG8_BAR; PG8_MMA(0, 0, At, B0); PG8_MMA(0, 1, At, B1); PG8_BAR; PG8_SCHED;
;             PG8_LDA(At, 0, 1); PG8_STAGE(PG8_SB(0, 0), b2, voffB); PG8_STAGE(PG8_SB(0, 1), b2 + hstepB, voffB); PG8_STAGE(PG8_SA(0, 0), a2, voffA);
;             PG8_WAIT_V(8); PG8_WAIT_L(0); PG8_BAR; PG8_MMA(1, 0, At, B0); PG8_MMA(1, 1, At, B1); PG8_BAR; PG8_SCHED;
.LBB1_574:
	s_add_u32 s14, s44, 0xfff80080
	s_addc_u32 s15, s45, -1
	s_add_i32 s82, 0, 0x10000
	s_cmp_eq_u32 s81, 28
	s_cselect_b32 s73, s43, s15
	s_cselect_b32 s72, s47, s14
	v_add_u32_e32 v148, s82, v151
	s_cselect_b32 s71, s61, s80
	s_cselect_b32 s70, s65, s79
	s_add_i32 s83, 0, 0x14000
	ds_read_b128 v[144:147], v148
	ds_read_b128 v[158:161], v148 offset:1024
	ds_read_b128 v[162:165], v148 offset:2048
	ds_read_b128 v[166:169], v148 offset:3072
	v_add_u32_e32 v148, s83, v151
	ds_read_b128 v[170:173], v148
	ds_read_b128 v[174:177], v148 offset:1024
	ds_read_b128 v[178:181], v148 offset:2048
	ds_read_b128 v[182:185], v148 offset:3072
	s_add_i32 m0, s57, 0xc000
	ds_read_b128 v[186:189], v156
	ds_read_b128 v[190:193], v156 offset:1024
	ds_read_b128 v[204:207], v156 offset:2048
	ds_read_b128 v[208:211], v156 offset:3072
	ds_read_b128 v[212:215], v156 offset:4096
	ds_read_b128 v[216:219], v156 offset:5120
	ds_read_b128 v[220:223], v156 offset:6144
	ds_read_b128 v[230:233], v156 offset:7168
	global_load_lds_dwordx4 v142, s[44:45]
	s_add_i32 m0, s57, 0xe000
	s_nop 0
	global_load_lds_dwordx4 v140, s[44:45]
	s_waitcnt vmcnt(8)
	s_waitcnt lgkmcnt(0)
	s_barrier
	s_setprio 1
	s_waitcnt lgkmcnt(0)
	v_mfma_f32_16x16x32_bf16 v[126:129], v[144:147], v[186:189], v[126:129]
	v_mfma_f32_16x16x32_bf16 v[122:125], v[162:165], v[186:189], v[122:125]
	v_mfma_f32_16x16x32_bf16 v[110:113], v[144:147], v[204:207], v[110:113]
	v_mfma_f32_16x16x32_bf16 v[106:109], v[162:165], v[204:207], v[106:109]
	v_mfma_f32_16x16x32_bf16 v[94:97], v[144:147], v[212:215], v[94:97]
	v_mfma_f32_16x16x32_bf16 v[90:93], v[162:165], v[212:215], v[90:93]
	v_mfma_f32_16x16x32_bf16 v[78:81], v[144:147], v[220:223], v[78:81]
	v_mfma_f32_16x16x32_bf16 v[74:77], v[162:165], v[220:223], v[74:77]
	v_mfma_f32_16x16x32_bf16 v[126:129], v[158:161], v[190:193], v[126:129]
	v_mfma_f32_16x16x32_bf16 v[122:125], v[166:169], v[190:193], v[122:125]
	v_mfma_f32_16x16x32_bf16 v[110:113], v[158:161], v[208:211], v[110:113]
	v_mfma_f32_16x16x32_bf16 v[106:109], v[166:169], v[208:211], v[106:109]
	v_mfma_f32_16x16x32_bf16 v[94:97], v[158:161], v[216:219], v[94:97]
	v_mfma_f32_16x16x32_bf16 v[90:93], v[166:169], v[216:219], v[90:93]
	v_mfma_f32_16x16x32_bf16 v[78:81], v[158:161], v[230:233], v[78:81]
	v_mfma_f32_16x16x32_bf16 v[74:77], v[166:169], v[230:233], v[74:77]
	s_setprio 0
	s_setprio 1
	v_mfma_f32_16x16x32_bf16 v[118:121], v[170:173], v[186:189], v[118:121]
	v_mfma_f32_16x16x32_bf16 v[114:117], v[178:181], v[186:189], v[114:117]
	v_mfma_f32_16x16x32_bf16 v[102:105], v[170:173], v[204:207], v[102:105]
	v_mfma_f32_16x16x32_bf16 v[98:101], v[178:181], v[204:207], v[98:101]
	v_mfma_f32_16x16x32_bf16 v[86:89], v[170:173], v[212:215], v[86:89]
	v_mfma_f32_16x16x32_bf16 v[82:85], v[178:181], v[212:215], v[82:85]
	v_mfma_f32_16x16x32_bf16 v[70:73], v[170:173], v[220:223], v[70:73]
	v_mfma_f32_16x16x32_bf16 v[66:69], v[178:181], v[220:223], v[66:69]
	v_mfma_f32_16x16x32_bf16 v[118:121], v[174:177], v[190:193], v[118:121]
	v_mfma_f32_16x16x32_bf16 v[114:117], v[182:185], v[190:193], v[114:117]
	v_mfma_f32_16x16x32_bf16 v[102:105], v[174:177], v[208:211], v[102:105]
	v_mfma_f32_16x16x32_bf16 v[98:101], v[182:185], v[208:211], v[98:101]
	v_mfma_f32_16x16x32_bf16 v[86:89], v[174:177], v[216:219], v[86:89]
	v_mfma_f32_16x16x32_bf16 v[82:85], v[182:185], v[216:219], v[82:85]
	v_mfma_f32_16x16x32_bf16 v[70:73], v[174:177], v[230:233], v[70:73]
	v_mfma_f32_16x16x32_bf16 v[66:69], v[182:185], v[230:233], v[66:69]
	s_setprio 0
	s_barrier
	s_add_i32 s14, s82, s56
	s_mov_b32 m0, s14
	ds_read_b128 v[186:189], v156 offset:16384
	ds_read_b128 v[190:193], v156 offset:17408
	ds_read_b128 v[204:207], v156 offset:18432
	ds_read_b128 v[208:211], v156 offset:19456
	ds_read_b128 v[212:215], v156 offset:20480
	ds_read_b128 v[216:219], v156 offset:21504
	ds_read_b128 v[220:223], v156 offset:22528
	ds_read_b128 v[230:233], v156 offset:23552
	global_load_lds_dwordx4 v0, s[70:71]
	s_add_i32 m0, s14, 0x2000
	s_add_u32 s14, s70, 0x80000
	s_addc_u32 s15, s71, 0
	s_add_i32 s82, s83, s56
	global_load_lds_dwordx4 v134, s[70:71]
	s_mov_b32 m0, s82
	s_nop 0
	global_load_lds_dwordx4 v0, s[14:15]
	s_add_i32 m0, s82, 0x2000
	s_nop 0
	global_load_lds_dwordx4 v134, s[14:15]
	s_mov_b32 m0, s57
	s_nop 0
	global_load_lds_dwordx4 v130, s[72:73]
	s_mov_b32 m0, s74
	s_nop 0
	global_load_lds_dwordx4 v132, s[72:73]
	s_waitcnt vmcnt(8)
	s_waitcnt lgkmcnt(0)
	s_barrier
	s_setprio 1
	s_waitcnt lgkmcnt(0)
	v_mfma_f32_16x16x32_bf16 v[62:65], v[144:147], v[186:189], v[62:65]
	v_mfma_f32_16x16x32_bf16 v[58:61], v[162:165], v[186:189], v[58:61]
	v_mfma_f32_16x16x32_bf16 v[46:49], v[144:147], v[204:207], v[46:49]
	v_mfma_f32_16x16x32_bf16 v[42:45], v[162:165], v[204:207], v[42:45]
	v_mfma_f32_16x16x32_bf16 v[30:33], v[144:147], v[212:215], v[30:33]
	v_mfma_f32_16x16x32_bf16 v[26:29], v[162:165], v[212:215], v[26:29]
	v_mfma_f32_16x16x32_bf16 v[14:17], v[144:147], v[220:223], v[14:17]
	v_mfma_f32_16x16x32_bf16 v[10:13], v[162:165], v[220:223], v[10:13]
	v_mfma_f32_16x16x32_bf16 v[62:65], v[158:161], v[190:193], v[62:65]
	v_mfma_f32_16x16x32_bf16 v[58:61], v[166:169], v[190:193], v[58:61]
	v_mfma_f32_16x16x32_bf16 v[46:49], v[158:161], v[208:211], v[46:49]
	v_mfma_f32_16x16x32_bf16 v[42:45], v[166:169], v[208:211], v[42:45]
	v_mfma_f32_16x16x32_bf16 v[30:33], v[158:161], v[216:219], v[30:33]
	v_mfma_f32_16x16x32_bf16 v[26:29], v[166:169], v[216:219], v[26:29]
	v_mfma_f32_16x16x32_bf16 v[14:17], v[158:161], v[230:233], v[14:17]
	v_mfma_f32_16x16x32_bf16 v[10:13], v[166:169], v[230:233], v[10:13]
	s_setprio 0
	s_setprio 1
	v_mfma_f32_16x16x32_bf16 v[54:57], v[170:173], v[186:189], v[54:57]
	v_mfma_f32_16x16x32_bf16 v[50:53], v[178:181], v[186:189], v[50:53]
	v_mfma_f32_16x16x32_bf16 v[38:41], v[170:173], v[204:207], v[38:41]
	v_mfma_f32_16x16x32_bf16 v[34:37], v[178:181], v[204:207], v[34:37]
	v_mfma_f32_16x16x32_bf16 v[22:25], v[170:173], v[212:215], v[22:25]
	v_mfma_f32_16x16x32_bf16 v[18:21], v[178:181], v[212:215], v[18:21]
	v_mfma_f32_16x16x32_bf16 v[6:9], v[170:173], v[220:223], v[6:9]
	v_mfma_f32_16x16x32_bf16 v[2:5], v[178:181], v[220:223], v[2:5]
	v_mfma_f32_16x16x32_bf16 v[54:57], v[174:177], v[190:193], v[54:57]
	v_mfma_f32_16x16x32_bf16 v[50:53], v[182:185], v[190:193], v[50:53]
	v_mfma_f32_16x16x32_bf16 v[38:41], v[174:177], v[208:211], v[38:41]
	v_mfma_f32_16x16x32_bf16 v[34:37], v[182:185], v[208:211], v[34:37]
	v_mfma_f32_16x16x32_bf16 v[22:25], v[174:177], v[216:219], v[22:25]
	v_mfma_f32_16x16x32_bf16 v[18:21], v[182:185], v[216:219], v[18:21]
	v_mfma_f32_16x16x32_bf16 v[6:9], v[174:177], v[230:233], v[6:9]
	v_mfma_f32_16x16x32_bf16 v[2:5], v[182:185], v[230:233], v[2:5]
	s_setprio 0
	s_barrier
; #define PG8_STAGE(bufoff, gbase, voff) do { _Pragma("unroll") for (int _i = 0; _i < 2; ++_i) \
;         __builtin_amdgcn_global_load_lds((const unsigned*)((const char*)(gbase) + (voff)[_i]), (LAS unsigned*)(lds + (bufoff) + ldsw + _i * 8192), 16, 0, 0); } while (0)
; #define PG8_LDA(dst, b, h) do { _Pragma("unroll") for (int m = 0; m < 4; ++m) _Pragma("unroll") for (int k = 0; k < 2; ++k) dst[m][k] = *(const LAS bf16x8*)(lds + PG8_SA(b, h) + aoff + m * 2048 + k * 1024); } while (0)
; #define PG8_LDB(dst, b, h) do { _Pragma("unroll") for (int n = 0; n < 2; ++n) _Pragma("unroll") for (int k = 0; k < 2; ++k) dst[n][k] = *(const LAS bf16x8*)(lds + PG8_SB(b, h) + boff + n * 2048 + k * 1024); } while (0)
; #define PG8_MMA(ai, bj, At, Bt) do { __builtin_amdgcn_s_setprio(1); _Pragma("unroll") for (int m = 0; m < 4; ++m) _Pragma("unroll") for (int n = 0; n < 2; ++n) _Pragma("unroll") for (int k = 0; k < 2; ++k) \
;         acc[ai][bj][m][n] = __builtin_amdgcn_mfma_f32_16x16x32_bf16(Bt[n][k], At[m][k], acc[ai][bj][m][n], 0, 0, 0); __builtin_amdgcn_s_setprio(0); } while (0)
; #define PG8_WAIT_V(n) asm volatile("s_waitcnt vmcnt(" #n ")" ::: "memory")
; #define PG8_WAIT_L(n) asm volatile("s_waitcnt lgkmcnt(" #n ")" ::: "memory")
; #define PG8_BAR __builtin_amdgcn_s_barrier()
; #define PG8_SCHED __builtin_amdgcn_sched_barrier(0)
; template <class Epi, class Sched>
; __device__ __forceinline__ void gemm_phase(LAS unsigned char* lds, const Gemm g, const Sched& S, const Epi& E, const int tid) {
;     ...
;             PG8_LDB(B0, 1, 0); PG8_LDB(B1, 1, 1); PG8_SCHED; PG8_LDA(At, 1, 0); PG8_STAGE(PG8_SA(0, 1), a2 + hstepA, voffA);
;             PG8_WAIT_V(8); PG8_WAIT_L(0); PG8_BAR; PG8_MMA(0, 0, At, B0); PG8_MMA(0, 1, At, B1); PG8_BAR; PG8_SCHED;
;             PG8_LDA(At, 1, 1); PG8_STAGE(PG8_SB(1, 0), b3, voffB); PG8_STAGE(PG8_SB(1, 1), b3 + hstepB, voffB); PG8_STAGE(PG8_SA(1, 0), a3, voffA);
;             PG8_WAIT_V(8); PG8_WAIT_L(0); PG8_BAR; PG8_MMA(1, 0, At, B0); PG8_MMA(1, 1, At, B1); PG8_BAR; PG8_SCHED;
;         }
	s_add_i32 s82, 0, 0x18000
	v_add_u32_e32 v157, s82, v151
	s_add_i32 s83, 0, 0x1c000
	ds_read_b128 v[144:147], v157
	ds_read_b128 v[158:161], v157 offset:1024
	ds_read_b128 v[162:165], v157 offset:2048
	ds_read_b128 v[166:169], v157 offset:3072
	v_add_u32_e32 v157, s83, v151
	ds_read_b128 v[170:173], v157
	ds_read_b128 v[174:177], v157 offset:1024
	ds_read_b128 v[178:181], v157 offset:2048
	ds_read_b128 v[182:185], v157 offset:3072
	s_add_u32 s14, s72, 0x80000
	s_addc_u32 s15, s73, 0
	s_mov_b32 m0, s75
	ds_read_b128 v[186:189], v156 offset:32768
	ds_read_b128 v[190:193], v156 offset:33792
	ds_read_b128 v[204:207], v156 offset:34816
	ds_read_b128 v[208:211], v156 offset:35840
	ds_read_b128 v[212:215], v156 offset:36864
	ds_read_b128 v[216:219], v156 offset:37888
	ds_read_b128 v[220:223], v156 offset:38912
	ds_read_b128 v[230:233], v156 offset:39936
	global_load_lds_dwordx4 v130, s[14:15]
	s_mov_b32 m0, s76
	s_nop 0
	global_load_lds_dwordx4 v132, s[14:15]
	s_waitcnt vmcnt(8)
	s_waitcnt lgkmcnt(0)
	s_barrier
	s_setprio 1
	s_waitcnt lgkmcnt(0)
	v_mfma_f32_16x16x32_bf16 v[126:129], v[144:147], v[186:189], v[126:129]
	v_mfma_f32_16x16x32_bf16 v[122:125], v[162:165], v[186:189], v[122:125]
	v_mfma_f32_16x16x32_bf16 v[110:113], v[144:147], v[204:207], v[110:113]
	v_mfma_f32_16x16x32_bf16 v[106:109], v[162:165], v[204:207], v[106:109]
	v_mfma_f32_16x16x32_bf16 v[94:97], v[144:147], v[212:215], v[94:97]
	v_mfma_f32_16x16x32_bf16 v[90:93], v[162:165], v[212:215], v[90:93]
	v_mfma_f32_16x16x32_bf16 v[78:81], v[144:147], v[220:223], v[78:81]
	v_mfma_f32_16x16x32_bf16 v[74:77], v[162:165], v[220:223], v[74:77]
	v_mfma_f32_16x16x32_bf16 v[126:129], v[158:161], v[190:193], v[126:129]
	v_mfma_f32_16x16x32_bf16 v[122:125], v[166:169], v[190:193], v[122:125]
	v_mfma_f32_16x16x32_bf16 v[110:113], v[158:161], v[208:211], v[110:113]
	v_mfma_f32_16x16x32_bf16 v[106:109], v[166:169], v[208:211], v[106:109]
	v_mfma_f32_16x16x32_bf16 v[94:97], v[158:161], v[216:219], v[94:97]
	v_mfma_f32_16x16x32_bf16 v[90:93], v[166:169], v[216:219], v[90:93]
	v_mfma_f32_16x16x32_bf16 v[78:81], v[158:161], v[230:233], v[78:81]
	v_mfma_f32_16x16x32_bf16 v[74:77], v[166:169], v[230:233], v[74:77]
	s_setprio 0
	s_setprio 1
	v_mfma_f32_16x16x32_bf16 v[118:121], v[170:173], v[186:189], v[118:121]
	v_mfma_f32_16x16x32_bf16 v[114:117], v[178:181], v[186:189], v[114:117]
	v_mfma_f32_16x16x32_bf16 v[102:105], v[170:173], v[204:207], v[102:105]
	v_mfma_f32_16x16x32_bf16 v[98:101], v[178:181], v[204:207], v[98:101]
	v_mfma_f32_16x16x32_bf16 v[86:89], v[170:173], v[212:215], v[86:89]
	v_mfma_f32_16x16x32_bf16 v[82:85], v[178:181], v[212:215], v[82:85]
	v_mfma_f32_16x16x32_bf16 v[70:73], v[170:173], v[220:223], v[70:73]
	v_mfma_f32_16x16x32_bf16 v[66:69], v[178:181], v[220:223], v[66:69]
	v_mfma_f32_16x16x32_bf16 v[118:121], v[174:177], v[190:193], v[118:121]
	v_mfma_f32_16x16x32_bf16 v[114:117], v[182:185], v[190:193], v[114:117]
	v_mfma_f32_16x16x32_bf16 v[102:105], v[174:177], v[208:211], v[102:105]
	v_mfma_f32_16x16x32_bf16 v[98:101], v[182:185], v[208:211], v[98:101]
	v_mfma_f32_16x16x32_bf16 v[86:89], v[174:177], v[216:219], v[86:89]
	v_mfma_f32_16x16x32_bf16 v[82:85], v[182:185], v[216:219], v[82:85]
	v_mfma_f32_16x16x32_bf16 v[70:73], v[174:177], v[230:233], v[70:73]
	v_mfma_f32_16x16x32_bf16 v[66:69], v[182:185], v[230:233], v[66:69]
	s_setprio 0
	s_barrier
	s_add_i32 s14, s82, s56
	s_add_u32 s100, s70, 0x80
	s_addc_u32 s101, s71, 0
	s_mov_b32 m0, s14
	ds_read_b128 v[186:189], v156 offset:49152
	ds_read_b128 v[190:193], v156 offset:50176
	ds_read_b128 v[204:207], v156 offset:51200
	ds_read_b128 v[208:211], v156 offset:52224
	ds_read_b128 v[212:215], v156 offset:53248
	ds_read_b128 v[216:219], v156 offset:54272
	ds_read_b128 v[220:223], v156 offset:55296
	ds_read_b128 v[230:233], v156 offset:56320
	global_load_lds_dwordx4 v0, s[100:101]
	s_add_i32 m0, s14, 0x2000
	s_add_u32 s14, s70, 0x80080
	s_addc_u32 s15, s71, 0
	s_add_i32 s70, s83, s56
	global_load_lds_dwordx4 v134, s[100:101]
	s_mov_b32 m0, s70
	s_nop 0
	global_load_lds_dwordx4 v0, s[14:15]
	s_add_i32 m0, s70, 0x2000
	s_nop 0
	global_load_lds_dwordx4 v134, s[14:15]
	s_add_u32 s100, s72, 0x80
	s_addc_u32 s101, s73, 0
	s_mov_b32 m0, s77
	s_nop 0
	global_load_lds_dwordx4 v130, s[100:101]
	s_mov_b32 m0, s78
	s_nop 0
	global_load_lds_dwordx4 v132, s[100:101]
	s_waitcnt vmcnt(8)
	s_waitcnt lgkmcnt(0)
	s_barrier
	s_setprio 1
	s_waitcnt lgkmcnt(0)
	v_mfma_f32_16x16x32_bf16 v[62:65], v[144:147], v[186:189], v[62:65]
	v_mfma_f32_16x16x32_bf16 v[58:61], v[162:165], v[186:189], v[58:61]
	v_mfma_f32_16x16x32_bf16 v[46:49], v[144:147], v[204:207], v[46:49]
	v_mfma_f32_16x16x32_bf16 v[42:45], v[162:165], v[204:207], v[42:45]
	v_mfma_f32_16x16x32_bf16 v[30:33], v[144:147], v[212:215], v[30:33]
	v_mfma_f32_16x16x32_bf16 v[26:29], v[162:165], v[212:215], v[26:29]
	v_mfma_f32_16x16x32_bf16 v[14:17], v[144:147], v[220:223], v[14:17]
	v_mfma_f32_16x16x32_bf16 v[10:13], v[162:165], v[220:223], v[10:13]
	v_mfma_f32_16x16x32_bf16 v[62:65], v[158:161], v[190:193], v[62:65]
	v_mfma_f32_16x16x32_bf16 v[58:61], v[166:169], v[190:193], v[58:61]
	v_mfma_f32_16x16x32_bf16 v[46:49], v[158:161], v[208:211], v[46:49]
	v_mfma_f32_16x16x32_bf16 v[42:45], v[166:169], v[208:211], v[42:45]
	v_mfma_f32_16x16x32_bf16 v[30:33], v[158:161], v[216:219], v[30:33]
	v_mfma_f32_16x16x32_bf16 v[26:29], v[166:169], v[216:219], v[26:29]
	v_mfma_f32_16x16x32_bf16 v[14:17], v[158:161], v[230:233], v[14:17]
	v_mfma_f32_16x16x32_bf16 v[10:13], v[166:169], v[230:233], v[10:13]
	s_setprio 0
	s_setprio 1
	v_mfma_f32_16x16x32_bf16 v[54:57], v[170:173], v[186:189], v[54:57]
	v_mfma_f32_16x16x32_bf16 v[50:53], v[178:181], v[186:189], v[50:53]
	v_mfma_f32_16x16x32_bf16 v[38:41], v[170:173], v[204:207], v[38:41]
	v_mfma_f32_16x16x32_bf16 v[34:37], v[178:181], v[204:207], v[34:37]
	v_mfma_f32_16x16x32_bf16 v[22:25], v[170:173], v[212:215], v[22:25]
	v_mfma_f32_16x16x32_bf16 v[18:21], v[178:181], v[212:215], v[18:21]
	v_mfma_f32_16x16x32_bf16 v[6:9], v[170:173], v[220:223], v[6:9]
	v_mfma_f32_16x16x32_bf16 v[2:5], v[178:181], v[220:223], v[2:5]
	v_mfma_f32_16x16x32_bf16 v[54:57], v[174:177], v[190:193], v[54:57]
	v_mfma_f32_16x16x32_bf16 v[50:53], v[182:185], v[190:193], v[50:53]
	v_mfma_f32_16x16x32_bf16 v[38:41], v[174:177], v[208:211], v[38:41]
	v_mfma_f32_16x16x32_bf16 v[34:37], v[182:185], v[208:211], v[34:37]
	v_mfma_f32_16x16x32_bf16 v[22:25], v[174:177], v[216:219], v[22:25]
	v_mfma_f32_16x16x32_bf16 v[18:21], v[182:185], v[216:219], v[18:21]
	v_mfma_f32_16x16x32_bf16 v[6:9], v[174:177], v[230:233], v[6:9]
	v_mfma_f32_16x16x32_bf16 v[2:5], v[182:185], v[230:233], v[2:5]
	s_setprio 0
	s_barrier
	s_add_i32 s81, s81, 2
	s_add_u32 s79, s79, 0x100
	s_addc_u32 s80, s80, 0
	s_add_u32 s44, s44, 0x100
	s_addc_u32 s45, s45, 0
	s_cmp_gt_u32 s81, 29
	s_cbranch_scc0 .LBB1_574
	s_and_b64 vcc, exec, s[36:37]
	s_cbranch_vccz .LBB1_577
	s_barrier

; #define PG8_STAGE(bufoff, gbase, voff) do { _Pragma("unroll") for (int _i = 0; _i < 2; ++_i) \
;         __builtin_amdgcn_global_load_lds((const unsigned*)((const char*)(gbase) + (voff)[_i]), (LAS unsigned*)(lds + (bufoff) + ldsw + _i * 8192), 16, 0, 0); } while (0)
; #define PG8_LDA(dst, b, h) do { _Pragma("unroll") for (int m = 0; m < 4; ++m) _Pragma("unroll") for (int k = 0; k < 2; ++k) dst[m][k] = *(const LAS bf16x8*)(lds + PG8_SA(b, h) + aoff + m * 2048 + k * 1024); } while (0)
; #define PG8_LDB(dst, b, h) do { _Pragma("unroll") for (int n = 0; n < 2; ++n) _Pragma("unroll") for (int k = 0; k < 2; ++k) dst[n][k] = *(const LAS bf16x8*)(lds + PG8_SB(b, h) + boff + n * 2048 + k * 1024); } while (0)
; #define PG8_MMA(ai, bj, At, Bt) do { __builtin_amdgcn_s_setprio(1); _Pragma("unroll") for (int m = 0; m < 4; ++m) _Pragma("unroll") for (int n = 0; n < 2; ++n) _Pragma("unroll") for (int k = 0; k < 2; ++k) \
;         acc[ai][bj][m][n] = __builtin_amdgcn_mfma_f32_16x16x32_bf16(Bt[n][k], At[m][k], acc[ai][bj][m][n], 0, 0, 0); __builtin_amdgcn_s_setprio(0); } while (0)
; #define PG8_WAIT_V(n) asm volatile("s_waitcnt vmcnt(" #n ")" ::: "memory")
; #define PG8_WAIT_L(n) asm volatile("s_waitcnt lgkmcnt(" #n ")" ::: "memory")
; #define PG8_BAR __builtin_amdgcn_s_barrier()
; #define PG8_SCHED __builtin_amdgcn_sched_barrier(0)
; template <class Epi, class Sched>
; __device__ __forceinline__ void gemm_phase(LAS unsigned char* lds, const Gemm g, const Sched& S, const Epi& E, const int tid) {
;     ...
;             const char* a1 = cA + (size_t)(t + 1) * kstep;
;             const char* a2 = last ? nA : cA + (size_t)(t + 2) * kstep; const char* b2 = last ? nB : cB + (size_t)(t + 2) * kstep;
;             const char* a3 = a2 + kstep; const char* b3 = b2 + kstep;
;             PG8_LDB(B0, 0, 0); PG8_LDB(B1, 0, 1); PG8_SCHED; PG8_LDA(At, 0, 0); PG8_STAGE(PG8_SA(1, 1), a1 + hstepA, voffA);
;             PG8_WAIT_V(8); PG8_WAIT_L(0); PG8_BAR; PG8_MMA(0, 0, At, B0); PG8_MMA(0, 1, At, B1); PG8_BAR; PG8_SCHED;
;             PG8_LDA(At, 0, 1); PG8_STAGE(PG8_SB(0, 0), b2, voffB); PG8_STAGE(PG8_SB(0, 1), b2 + hstepB, voffB); PG8_STAGE(PG8_SA(0, 0), a2, voffA);
;             PG8_WAIT_V(8); PG8_WAIT_L(0); PG8_BAR; PG8_MMA(1, 0, At, B0); PG8_MMA(1, 1, At, B1); PG8_BAR; PG8_SCHED;
.LBB1_724:
	s_add_u32 s14, s48, 0xfff80080
	s_addc_u32 s15, s49, -1
	s_add_i32 s72, 0, 0x10000
	s_cmp_eq_u32 s71, 28
	s_cselect_b32 s57, s37, s15
	s_cselect_b32 s56, s41, s14
	v_add_u32_e32 v144, s72, v147
	s_cselect_b32 s53, s27, s70
	s_cselect_b32 s52, s68, s69
	s_add_i32 s73, 0, 0x14000
	ds_read_b128 v[140:143], v144
	ds_read_b128 v[158:161], v144 offset:1024
	ds_read_b128 v[162:165], v144 offset:2048
	ds_read_b128 v[166:169], v144 offset:3072
	v_add_u32_e32 v144, s73, v147
	ds_read_b128 v[170:173], v144
	ds_read_b128 v[174:177], v144 offset:1024
	ds_read_b128 v[178:181], v144 offset:2048
	ds_read_b128 v[182:185], v144 offset:3072
	s_add_i32 m0, s47, 0xc000
	ds_read_b128 v[186:189], v156
	ds_read_b128 v[190:193], v156 offset:1024
	ds_read_b128 v[204:207], v156 offset:2048
	ds_read_b128 v[208:211], v156 offset:3072
	ds_read_b128 v[212:215], v156 offset:4096
	ds_read_b128 v[216:219], v156 offset:5120
	ds_read_b128 v[220:223], v156 offset:6144
	ds_read_b128 v[230:233], v156 offset:7168
	global_load_lds_dwordx4 v138, s[48:49]
	s_add_i32 m0, s47, 0xe000
	s_nop 0
	global_load_lds_dwordx4 v136, s[48:49]
	s_waitcnt vmcnt(8)
	s_waitcnt lgkmcnt(0)
	s_barrier
	s_setprio 1
	s_waitcnt lgkmcnt(0)
	v_mfma_f32_16x16x32_bf16 v[126:129], v[140:143], v[186:189], v[126:129]
	v_mfma_f32_16x16x32_bf16 v[122:125], v[162:165], v[186:189], v[122:125]
	v_mfma_f32_16x16x32_bf16 v[110:113], v[140:143], v[204:207], v[110:113]
	v_mfma_f32_16x16x32_bf16 v[106:109], v[162:165], v[204:207], v[106:109]
	v_mfma_f32_16x16x32_bf16 v[94:97], v[140:143], v[212:215], v[94:97]
	v_mfma_f32_16x16x32_bf16 v[90:93], v[162:165], v[212:215], v[90:93]
	v_mfma_f32_16x16x32_bf16 v[78:81], v[140:143], v[220:223], v[78:81]
	v_mfma_f32_16x16x32_bf16 v[74:77], v[162:165], v[220:223], v[74:77]
	v_mfma_f32_16x16x32_bf16 v[126:129], v[158:161], v[190:193], v[126:129]
	v_mfma_f32_16x16x32_bf16 v[122:125], v[166:169], v[190:193], v[122:125]
	v_mfma_f32_16x16x32_bf16 v[110:113], v[158:161], v[208:211], v[110:113]
	v_mfma_f32_16x16x32_bf16 v[106:109], v[166:169], v[208:211], v[106:109]
	v_mfma_f32_16x16x32_bf16 v[94:97], v[158:161], v[216:219], v[94:97]
	v_mfma_f32_16x16x32_bf16 v[90:93], v[166:169], v[216:219], v[90:93]
	v_mfma_f32_16x16x32_bf16 v[78:81], v[158:161], v[230:233], v[78:81]
	v_mfma_f32_16x16x32_bf16 v[74:77], v[166:169], v[230:233], v[74:77]
	s_setprio 0
	s_setprio 1
	v_mfma_f32_16x16x32_bf16 v[118:121], v[170:173], v[186:189], v[118:121]
	v_mfma_f32_16x16x32_bf16 v[114:117], v[178:181], v[186:189], v[114:117]
	v_mfma_f32_16x16x32_bf16 v[102:105], v[170:173], v[204:207], v[102:105]
	v_mfma_f32_16x16x32_bf16 v[98:101], v[178:181], v[204:207], v[98:101]
	v_mfma_f32_16x16x32_bf16 v[86:89], v[170:173], v[212:215], v[86:89]
	v_mfma_f32_16x16x32_bf16 v[82:85], v[178:181], v[212:215], v[82:85]
	v_mfma_f32_16x16x32_bf16 v[70:73], v[170:173], v[220:223], v[70:73]
	v_mfma_f32_16x16x32_bf16 v[66:69], v[178:181], v[220:223], v[66:69]
	v_mfma_f32_16x16x32_bf16 v[118:121], v[174:177], v[190:193], v[118:121]
	v_mfma_f32_16x16x32_bf16 v[114:117], v[182:185], v[190:193], v[114:117]
	v_mfma_f32_16x16x32_bf16 v[102:105], v[174:177], v[208:211], v[102:105]
	v_mfma_f32_16x16x32_bf16 v[98:101], v[182:185], v[208:211], v[98:101]
	v_mfma_f32_16x16x32_bf16 v[86:89], v[174:177], v[216:219], v[86:89]
	v_mfma_f32_16x16x32_bf16 v[82:85], v[182:185], v[216:219], v[82:85]
	v_mfma_f32_16x16x32_bf16 v[70:73], v[174:177], v[230:233], v[70:73]
	v_mfma_f32_16x16x32_bf16 v[66:69], v[182:185], v[230:233], v[66:69]
	s_setprio 0
	s_barrier
	s_add_i32 s14, s72, s62
	s_mov_b32 m0, s14
	ds_read_b128 v[186:189], v156 offset:16384
	ds_read_b128 v[190:193], v156 offset:17408
	ds_read_b128 v[204:207], v156 offset:18432
	ds_read_b128 v[208:211], v156 offset:19456
	ds_read_b128 v[212:215], v156 offset:20480
	ds_read_b128 v[216:219], v156 offset:21504
	ds_read_b128 v[220:223], v156 offset:22528
	ds_read_b128 v[230:233], v156 offset:23552
	global_load_lds_dwordx4 v0, s[52:53]
	s_add_i32 m0, s14, 0x2000
	s_add_u32 s14, s52, 0x80000
	s_addc_u32 s15, s53, 0
	s_add_i32 s72, s73, s62
	global_load_lds_dwordx4 v134, s[52:53]
	s_mov_b32 m0, s72
	s_nop 0
	global_load_lds_dwordx4 v0, s[14:15]
	s_add_i32 m0, s72, 0x2000
	s_nop 0
	global_load_lds_dwordx4 v134, s[14:15]
	s_mov_b32 m0, s47
	s_nop 0
	global_load_lds_dwordx4 v130, s[56:57]
	s_mov_b32 m0, s63
	s_nop 0
	global_load_lds_dwordx4 v132, s[56:57]
	s_waitcnt vmcnt(8)
	s_waitcnt lgkmcnt(0)
	s_barrier
	s_setprio 1
	s_waitcnt lgkmcnt(0)
	v_mfma_f32_16x16x32_bf16 v[62:65], v[140:143], v[186:189], v[62:65]
	v_mfma_f32_16x16x32_bf16 v[58:61], v[162:165], v[186:189], v[58:61]
	v_mfma_f32_16x16x32_bf16 v[46:49], v[140:143], v[204:207], v[46:49]
	v_mfma_f32_16x16x32_bf16 v[42:45], v[162:165], v[204:207], v[42:45]
	v_mfma_f32_16x16x32_bf16 v[30:33], v[140:143], v[212:215], v[30:33]
	v_mfma_f32_16x16x32_bf16 v[26:29], v[162:165], v[212:215], v[26:29]
	v_mfma_f32_16x16x32_bf16 v[14:17], v[140:143], v[220:223], v[14:17]
	v_mfma_f32_16x16x32_bf16 v[10:13], v[162:165], v[220:223], v[10:13]
	v_mfma_f32_16x16x32_bf16 v[62:65], v[158:161], v[190:193], v[62:65]
	v_mfma_f32_16x16x32_bf16 v[58:61], v[166:169], v[190:193], v[58:61]
	v_mfma_f32_16x16x32_bf16 v[46:49], v[158:161], v[208:211], v[46:49]
	v_mfma_f32_16x16x32_bf16 v[42:45], v[166:169], v[208:211], v[42:45]
	v_mfma_f32_16x16x32_bf16 v[30:33], v[158:161], v[216:219], v[30:33]
	v_mfma_f32_16x16x32_bf16 v[26:29], v[166:169], v[216:219], v[26:29]
	v_mfma_f32_16x16x32_bf16 v[14:17], v[158:161], v[230:233], v[14:17]
	v_mfma_f32_16x16x32_bf16 v[10:13], v[166:169], v[230:233], v[10:13]
	s_setprio 0
	s_setprio 1
	v_mfma_f32_16x16x32_bf16 v[54:57], v[170:173], v[186:189], v[54:57]
	v_mfma_f32_16x16x32_bf16 v[50:53], v[178:181], v[186:189], v[50:53]
	v_mfma_f32_16x16x32_bf16 v[38:41], v[170:173], v[204:207], v[38:41]
	v_mfma_f32_16x16x32_bf16 v[34:37], v[178:181], v[204:207], v[34:37]
	v_mfma_f32_16x16x32_bf16 v[22:25], v[170:173], v[212:215], v[22:25]
	v_mfma_f32_16x16x32_bf16 v[18:21], v[178:181], v[212:215], v[18:21]
	v_mfma_f32_16x16x32_bf16 v[6:9], v[170:173], v[220:223], v[6:9]
	v_mfma_f32_16x16x32_bf16 v[2:5], v[178:181], v[220:223], v[2:5]
	v_mfma_f32_16x16x32_bf16 v[54:57], v[174:177], v[190:193], v[54:57]
	v_mfma_f32_16x16x32_bf16 v[50:53], v[182:185], v[190:193], v[50:53]
	v_mfma_f32_16x16x32_bf16 v[38:41], v[174:177], v[208:211], v[38:41]
	v_mfma_f32_16x16x32_bf16 v[34:37], v[182:185], v[208:211], v[34:37]
	v_mfma_f32_16x16x32_bf16 v[22:25], v[174:177], v[216:219], v[22:25]
	v_mfma_f32_16x16x32_bf16 v[18:21], v[182:185], v[216:219], v[18:21]
	v_mfma_f32_16x16x32_bf16 v[6:9], v[174:177], v[230:233], v[6:9]
	v_mfma_f32_16x16x32_bf16 v[2:5], v[182:185], v[230:233], v[2:5]
	s_setprio 0
	s_barrier
; #define PG8_STAGE(bufoff, gbase, voff) do { _Pragma("unroll") for (int _i = 0; _i < 2; ++_i) \
;         __builtin_amdgcn_global_load_lds((const unsigned*)((const char*)(gbase) + (voff)[_i]), (LAS unsigned*)(lds + (bufoff) + ldsw + _i * 8192), 16, 0, 0); } while (0)
; #define PG8_LDA(dst, b, h) do { _Pragma("unroll") for (int m = 0; m < 4; ++m) _Pragma("unroll") for (int k = 0; k < 2; ++k) dst[m][k] = *(const LAS bf16x8*)(lds + PG8_SA(b, h) + aoff + m * 2048 + k * 1024); } while (0)
; #define PG8_LDB(dst, b, h) do { _Pragma("unroll") for (int n = 0; n < 2; ++n) _Pragma("unroll") for (int k = 0; k < 2; ++k) dst[n][k] = *(const LAS bf16x8*)(lds + PG8_SB(b, h) + boff + n * 2048 + k * 1024); } while (0)
; #define PG8_MMA(ai, bj, At, Bt) do { __builtin_amdgcn_s_setprio(1); _Pragma("unroll") for (int m = 0; m < 4; ++m) _Pragma("unroll") for (int n = 0; n < 2; ++n) _Pragma("unroll") for (int k = 0; k < 2; ++k) \
;         acc[ai][bj][m][n] = __builtin_amdgcn_mfma_f32_16x16x32_bf16(Bt[n][k], At[m][k], acc[ai][bj][m][n], 0, 0, 0); __builtin_amdgcn_s_setprio(0); } while (0)
; #define PG8_WAIT_V(n) asm volatile("s_waitcnt vmcnt(" #n ")" ::: "memory")
; #define PG8_WAIT_L(n) asm volatile("s_waitcnt lgkmcnt(" #n ")" ::: "memory")
; #define PG8_BAR __builtin_amdgcn_s_barrier()
; #define PG8_SCHED __builtin_amdgcn_sched_barrier(0)
; template <class Epi, class Sched>
; __device__ __forceinline__ void gemm_phase(LAS unsigned char* lds, const Gemm g, const Sched& S, const Epi& E, const int tid) {
;     ...
;             PG8_LDB(B0, 1, 0); PG8_LDB(B1, 1, 1); PG8_SCHED; PG8_LDA(At, 1, 0); PG8_STAGE(PG8_SA(0, 1), a2 + hstepA, voffA);
;             PG8_WAIT_V(8); PG8_WAIT_L(0); PG8_BAR; PG8_MMA(0, 0, At, B0); PG8_MMA(0, 1, At, B1); PG8_BAR; PG8_SCHED;
;             PG8_LDA(At, 1, 1); PG8_STAGE(PG8_SB(1, 0), b3, voffB); PG8_STAGE(PG8_SB(1, 1), b3 + hstepB, voffB); PG8_STAGE(PG8_SA(1, 0), a3, voffA);
;             PG8_WAIT_V(8); PG8_WAIT_L(0); PG8_BAR; PG8_MMA(1, 0, At, B0); PG8_MMA(1, 1, At, B1); PG8_BAR; PG8_SCHED;
;         }
	s_add_i32 s72, 0, 0x18000
	v_add_u32_e32 v157, s72, v147
	s_add_i32 s73, 0, 0x1c000
	ds_read_b128 v[140:143], v157
	ds_read_b128 v[158:161], v157 offset:1024
	ds_read_b128 v[162:165], v157 offset:2048
	ds_read_b128 v[166:169], v157 offset:3072
	v_add_u32_e32 v157, s73, v147
	ds_read_b128 v[170:173], v157
	ds_read_b128 v[174:177], v157 offset:1024
	ds_read_b128 v[178:181], v157 offset:2048
	ds_read_b128 v[182:185], v157 offset:3072
	s_add_u32 s14, s56, 0x80000
	s_addc_u32 s15, s57, 0
	s_mov_b32 m0, s64
	ds_read_b128 v[186:189], v156 offset:32768
	ds_read_b128 v[190:193], v156 offset:33792
	ds_read_b128 v[204:207], v156 offset:34816
	ds_read_b128 v[208:211], v156 offset:35840
	ds_read_b128 v[212:215], v156 offset:36864
	ds_read_b128 v[216:219], v156 offset:37888
	ds_read_b128 v[220:223], v156 offset:38912
	ds_read_b128 v[230:233], v156 offset:39936
	global_load_lds_dwordx4 v130, s[14:15]
	s_mov_b32 m0, s65
	s_nop 0
	global_load_lds_dwordx4 v132, s[14:15]
	s_waitcnt vmcnt(8)
	s_waitcnt lgkmcnt(0)
	s_barrier
	s_setprio 1
	s_waitcnt lgkmcnt(0)
	v_mfma_f32_16x16x32_bf16 v[126:129], v[140:143], v[186:189], v[126:129]
	v_mfma_f32_16x16x32_bf16 v[122:125], v[162:165], v[186:189], v[122:125]
	v_mfma_f32_16x16x32_bf16 v[110:113], v[140:143], v[204:207], v[110:113]
	v_mfma_f32_16x16x32_bf16 v[106:109], v[162:165], v[204:207], v[106:109]
	v_mfma_f32_16x16x32_bf16 v[94:97], v[140:143], v[212:215], v[94:97]
	v_mfma_f32_16x16x32_bf16 v[90:93], v[162:165], v[212:215], v[90:93]
	v_mfma_f32_16x16x32_bf16 v[78:81], v[140:143], v[220:223], v[78:81]
	v_mfma_f32_16x16x32_bf16 v[74:77], v[162:165], v[220:223], v[74:77]
	v_mfma_f32_16x16x32_bf16 v[126:129], v[158:161], v[190:193], v[126:129]
	v_mfma_f32_16x16x32_bf16 v[122:125], v[166:169], v[190:193], v[122:125]
	v_mfma_f32_16x16x32_bf16 v[110:113], v[158:161], v[208:211], v[110:113]
	v_mfma_f32_16x16x32_bf16 v[106:109], v[166:169], v[208:211], v[106:109]
	v_mfma_f32_16x16x32_bf16 v[94:97], v[158:161], v[216:219], v[94:97]
	v_mfma_f32_16x16x32_bf16 v[90:93], v[166:169], v[216:219], v[90:93]
	v_mfma_f32_16x16x32_bf16 v[78:81], v[158:161], v[230:233], v[78:81]
	v_mfma_f32_16x16x32_bf16 v[74:77], v[166:169], v[230:233], v[74:77]
	s_setprio 0
	s_setprio 1
	v_mfma_f32_16x16x32_bf16 v[118:121], v[170:173], v[186:189], v[118:121]
	v_mfma_f32_16x16x32_bf16 v[114:117], v[178:181], v[186:189], v[114:117]
	v_mfma_f32_16x16x32_bf16 v[102:105], v[170:173], v[204:207], v[102:105]
	v_mfma_f32_16x16x32_bf16 v[98:101], v[178:181], v[204:207], v[98:101]
	v_mfma_f32_16x16x32_bf16 v[86:89], v[170:173], v[212:215], v[86:89]
	v_mfma_f32_16x16x32_bf16 v[82:85], v[178:181], v[212:215], v[82:85]
	v_mfma_f32_16x16x32_bf16 v[70:73], v[170:173], v[220:223], v[70:73]
	v_mfma_f32_16x16x32_bf16 v[66:69], v[178:181], v[220:223], v[66:69]
	v_mfma_f32_16x16x32_bf16 v[118:121], v[174:177], v[190:193], v[118:121]
	v_mfma_f32_16x16x32_bf16 v[114:117], v[182:185], v[190:193], v[114:117]
	v_mfma_f32_16x16x32_bf16 v[102:105], v[174:177], v[208:211], v[102:105]
	v_mfma_f32_16x16x32_bf16 v[98:101], v[182:185], v[208:211], v[98:101]
	v_mfma_f32_16x16x32_bf16 v[86:89], v[174:177], v[216:219], v[86:89]
	v_mfma_f32_16x16x32_bf16 v[82:85], v[182:185], v[216:219], v[82:85]
	v_mfma_f32_16x16x32_bf16 v[70:73], v[174:177], v[230:233], v[70:73]
	v_mfma_f32_16x16x32_bf16 v[66:69], v[182:185], v[230:233], v[66:69]
	s_setprio 0
	s_barrier
	s_add_i32 s14, s72, s62
	s_add_u32 s100, s52, 0x80
	s_addc_u32 s101, s53, 0
	s_mov_b32 m0, s14
	ds_read_b128 v[186:189], v156 offset:49152
	ds_read_b128 v[190:193], v156 offset:50176
	ds_read_b128 v[204:207], v156 offset:51200
	ds_read_b128 v[208:211], v156 offset:52224
	ds_read_b128 v[212:215], v156 offset:53248
	ds_read_b128 v[216:219], v156 offset:54272
	ds_read_b128 v[220:223], v156 offset:55296
	ds_read_b128 v[230:233], v156 offset:56320
	global_load_lds_dwordx4 v0, s[100:101]
	s_add_i32 m0, s14, 0x2000
	s_add_u32 s14, s52, 0x80080
	s_addc_u32 s15, s53, 0
	s_add_i32 s52, s73, s62
	global_load_lds_dwordx4 v134, s[100:101]
	s_mov_b32 m0, s52
	s_nop 0
	global_load_lds_dwordx4 v0, s[14:15]
	s_add_i32 m0, s52, 0x2000
	s_nop 0
	global_load_lds_dwordx4 v134, s[14:15]
	s_add_u32 s100, s56, 0x80
	s_addc_u32 s101, s57, 0
	s_mov_b32 m0, s66
	s_nop 0
	global_load_lds_dwordx4 v130, s[100:101]
	s_mov_b32 m0, s67
	s_nop 0
	global_load_lds_dwordx4 v132, s[100:101]
	s_waitcnt vmcnt(8)
	s_waitcnt lgkmcnt(0)
	s_barrier
	s_setprio 1
	s_waitcnt lgkmcnt(0)
	v_mfma_f32_16x16x32_bf16 v[62:65], v[140:143], v[186:189], v[62:65]
	v_mfma_f32_16x16x32_bf16 v[58:61], v[162:165], v[186:189], v[58:61]
	v_mfma_f32_16x16x32_bf16 v[46:49], v[140:143], v[204:207], v[46:49]
	v_mfma_f32_16x16x32_bf16 v[42:45], v[162:165], v[204:207], v[42:45]
	v_mfma_f32_16x16x32_bf16 v[30:33], v[140:143], v[212:215], v[30:33]
	v_mfma_f32_16x16x32_bf16 v[26:29], v[162:165], v[212:215], v[26:29]
	v_mfma_f32_16x16x32_bf16 v[14:17], v[140:143], v[220:223], v[14:17]
	v_mfma_f32_16x16x32_bf16 v[10:13], v[162:165], v[220:223], v[10:13]
	v_mfma_f32_16x16x32_bf16 v[62:65], v[158:161], v[190:193], v[62:65]
	v_mfma_f32_16x16x32_bf16 v[58:61], v[166:169], v[190:193], v[58:61]
	v_mfma_f32_16x16x32_bf16 v[46:49], v[158:161], v[208:211], v[46:49]
	v_mfma_f32_16x16x32_bf16 v[42:45], v[166:169], v[208:211], v[42:45]
	v_mfma_f32_16x16x32_bf16 v[30:33], v[158:161], v[216:219], v[30:33]
	v_mfma_f32_16x16x32_bf16 v[26:29], v[166:169], v[216:219], v[26:29]
	v_mfma_f32_16x16x32_bf16 v[14:17], v[158:161], v[230:233], v[14:17]
	v_mfma_f32_16x16x32_bf16 v[10:13], v[166:169], v[230:233], v[10:13]
	s_setprio 0
	s_setprio 1
	v_mfma_f32_16x16x32_bf16 v[54:57], v[170:173], v[186:189], v[54:57]
	v_mfma_f32_16x16x32_bf16 v[50:53], v[178:181], v[186:189], v[50:53]
	v_mfma_f32_16x16x32_bf16 v[38:41], v[170:173], v[204:207], v[38:41]
	v_mfma_f32_16x16x32_bf16 v[34:37], v[178:181], v[204:207], v[34:37]
	v_mfma_f32_16x16x32_bf16 v[22:25], v[170:173], v[212:215], v[22:25]
	v_mfma_f32_16x16x32_bf16 v[18:21], v[178:181], v[212:215], v[18:21]
	v_mfma_f32_16x16x32_bf16 v[6:9], v[170:173], v[220:223], v[6:9]
	v_mfma_f32_16x16x32_bf16 v[2:5], v[178:181], v[220:223], v[2:5]
	v_mfma_f32_16x16x32_bf16 v[54:57], v[174:177], v[190:193], v[54:57]
	v_mfma_f32_16x16x32_bf16 v[50:53], v[182:185], v[190:193], v[50:53]
	v_mfma_f32_16x16x32_bf16 v[38:41], v[174:177], v[208:211], v[38:41]
	v_mfma_f32_16x16x32_bf16 v[34:37], v[182:185], v[208:211], v[34:37]
	v_mfma_f32_16x16x32_bf16 v[22:25], v[174:177], v[216:219], v[22:25]
	v_mfma_f32_16x16x32_bf16 v[18:21], v[182:185], v[216:219], v[18:21]
	v_mfma_f32_16x16x32_bf16 v[6:9], v[174:177], v[230:233], v[6:9]
	v_mfma_f32_16x16x32_bf16 v[2:5], v[182:185], v[230:233], v[2:5]
	s_setprio 0
	s_barrier
	s_add_i32 s71, s71, 2
	s_add_u32 s69, s69, 0x100
	s_addc_u32 s70, s70, 0
	s_add_u32 s48, s48, 0x100
	s_addc_u32 s49, s49, 0
	s_cmp_gt_u32 s71, 29
	s_cbranch_scc0 .LBB1_724
	s_and_b64 vcc, exec, s[6:7]
	s_cbranch_vccz .LBB1_727
	s_barrier

; __global__ void __launch_bounds__(512, 2) mega(Args args) {
;     extern __shared__ __attribute__((aligned(16))) unsigned char lds_raw[];
	.amdhsa_kernel _Z4mega4Args
		.amdhsa_group_segment_fixed_size 0
		.amdhsa_private_segment_fixed_size 0
		.amdhsa_kernarg_size 456
		.amdhsa_user_sgpr_count 2
		.amdhsa_user_sgpr_dispatch_ptr 0
		.amdhsa_user_sgpr_queue_ptr 0
		.amdhsa_user_sgpr_kernarg_segment_ptr 1
		.amdhsa_user_sgpr_dispatch_id 0
		.amdhsa_user_sgpr_kernarg_preload_length 0
		.amdhsa_user_sgpr_kernarg_preload_offset 0
		.amdhsa_user_sgpr_private_segment_size 0
		.amdhsa_uses_dynamic_stack 0
		.amdhsa_enable_private_segment 0
		.amdhsa_system_sgpr_workgroup_id_x 1
		.amdhsa_system_sgpr_workgroup_id_y 0
		.amdhsa_system_sgpr_workgroup_id_z 0
		.amdhsa_system_sgpr_workgroup_info 0
		.amdhsa_system_vgpr_workitem_id 2
		.amdhsa_next_free_vgpr 256
		.amdhsa_next_free_sgpr 102
		.amdhsa_accum_offset 256
		.amdhsa_reserve_vcc 1
		.amdhsa_float_round_mode_32 0
		.amdhsa_float_round_mode_16_64 0
		.amdhsa_float_denorm_mode_32 3
		.amdhsa_float_denorm_mode_16_64 3
		.amdhsa_dx10_clamp 1
		.amdhsa_ieee_mode 1
		.amdhsa_fp16_overflow 0
		.amdhsa_tg_split 0
		.amdhsa_exception_fp_ieee_invalid_op 0
		.amdhsa_exception_fp_denorm_src 0
		.amdhsa_exception_fp_ieee_div_zero 0
		.amdhsa_exception_fp_ieee_overflow 0
		.amdhsa_exception_fp_ieee_underflow 0
		.amdhsa_exception_fp_ieee_inexact 0
		.amdhsa_exception_int_div_zero 0
	.end_amdhsa_kernel

; __global__ void __launch_bounds__(256) naive_diff_attn(bf16_t* proj, const bf16_t* VT, const float* gq, const float* gk, const float* lv, const float* gsub, int layer, int pad) {
;     __shared__ float sQ[2][32][65], sK[2][32][65], sV[32][129], sP[2][32][33];
; __global__ void __launch_bounds__(512, 2) mega(Args args) {
;     extern __shared__ __attribute__((aligned(16))) unsigned char lds_raw[];
amdhsa.kernels:
  - .agpr_count:     57
    .args:
      - .address_space:  global
        .offset:         0
        .size:           8
        .value_kind:     global_buffer
      - .address_space:  global
        .offset:         8
        .size:           8
        .value_kind:     global_buffer
      - .address_space:  global
        .offset:         16
        .size:           8
        .value_kind:     global_buffer
      - .address_space:  global
        .offset:         24
        .size:           8
        .value_kind:     global_buffer
      - .address_space:  global
        .offset:         32
        .size:           8
        .value_kind:     global_buffer
      - .address_space:  global
        .offset:         40
        .size:           8
        .value_kind:     global_buffer
      - .offset:         48
        .size:           4
        .value_kind:     by_value
      - .offset:         52
        .size:           4
        .value_kind:     by_value
    .group_segment_fixed_size: 58240
    .kernarg_segment_align: 8
    .kernarg_segment_size: 56
    .language:       OpenCL C
    .language_version:
      - 2
      - 0
    .max_flat_workgroup_size: 256
    .name:           _Z15naive_diff_attnPtPKtPKfS3_S3_S3_ii
    .private_segment_fixed_size: 0
    .sgpr_count:     44
    .sgpr_spill_count: 0
    .symbol:         _Z15naive_diff_attnPtPKtPKfS3_S3_S3_ii.kd
    .uniform_work_group_size: 1
    .uses_dynamic_stack: false
    .vgpr_count:     313
    .vgpr_spill_count: 0
    .wavefront_size: 64
  - .agpr_count:     0
    .args:
      - .offset:         0
        .size:           200
        .value_kind:     by_value
      - .offset:         200
        .size:           4
        .value_kind:     hidden_block_count_x
      - .offset:         204
        .size:           4
        .value_kind:     hidden_block_count_y
      - .offset:         208
        .size:           4
        .value_kind:     hidden_block_count_z
      - .offset:         212
        .size:           2
        .value_kind:     hidden_group_size_x
      - .offset:         214
        .size:           2
        .value_kind:     hidden_group_size_y
      - .offset:         216
        .size:           2
        .value_kind:     hidden_group_size_z
      - .offset:         218
        .size:           2
        .value_kind:     hidden_remainder_x
      - .offset:         220
        .size:           2
        .value_kind:     hidden_remainder_y
      - .offset:         222
        .size:           2
        .value_kind:     hidden_remainder_z
      - .offset:         240
        .size:           8
        .value_kind:     hidden_global_offset_x
      - .offset:         248
        .size:           8
        .value_kind:     hidden_global_offset_y
      - .offset:         256
        .size:           8
        .value_kind:     hidden_global_offset_z
      - .offset:         264
        .size:           2
        .value_kind:     hidden_grid_dims
      - .offset:         288
        .size:           8
        .value_kind:     hidden_multigrid_sync_arg
      - .offset:         320
        .size:           4
        .value_kind:     hidden_dynamic_lds_size
    .group_segment_fixed_size: 0
    .kernarg_segment_align: 8
    .kernarg_segment_size: 456
    .language:       OpenCL C
    .language_version:
      - 2
      - 0
    .max_flat_workgroup_size: 512
    .name:           _Z4mega4Args
    .private_segment_fixed_size: 0
    .sgpr_count:     108
    .sgpr_spill_count: 215
    .symbol:         _Z4mega4Args.kd
    .uniform_work_group_size: 1
    .uses_dynamic_stack: false
    .vgpr_count:     256
    .vgpr_spill_count: 0
    .wavefront_size: 64
  - .agpr_count:     16
    .args:
      - .address_space:  global
        .offset:         0
        .size:           8
        .value_kind:     global_buffer
      - .address_space:  global
        .offset:         8
        .size:           8
        .value_kind:     global_buffer
      - .offset:         16
        .size:           40
        .value_kind:     by_value
      - .offset:         56
        .size:           4
        .value_kind:     by_value
      - .offset:         60
        .size:           4
        .value_kind:     by_value
      - .offset:         64
        .size:           4
        .value_kind:     by_value
      - .offset:         68
        .size:           4
        .value_kind:     by_value
      - .offset:         72
        .size:           4
        .value_kind:     by_value
      - .offset:         76
        .size:           4
        .value_kind:     by_value
    .group_segment_fixed_size: 0
    .kernarg_segment_align: 8
    .kernarg_segment_size: 80
    .language:       OpenCL C
    .language_version:
      - 2
      - 0
    .max_flat_workgroup_size: 256
    .name:           _Z10naive_gemmI3EInEvPKtS2_T_iiiiii
    .private_segment_fixed_size: 0
    .sgpr_count:     41
    .sgpr_spill_count: 0
    .symbol:         _Z10naive_gemmI3EInEvPKtS2_T_iiiiii.kd
    .uniform_work_group_size: 1
    .uses_dynamic_stack: false
    .vgpr_count:     68
    .vgpr_spill_count: 0
    .wavefront_size: 64
;     __device__ __forceinline__ float* target(int row, int col0) const { return (qss && col0 >= C_XQ && col0 < C_G) ? qss + row * 4 + ((col0 - C_XQ) >> 8) : nullptr; }
;     __device__ __forceinline__ float rowscale(int row) const { return rs_of(ss[row], 1.f / DM); }
;     __device__ __forceinline__ float rowscale(int row) const { return rs_of(ssmem[row], 1.f / DM); }
; template <class E> __global__ void __launch_bounds__(256) naive_gemm(const bf16_t* A, const bf16_t* Bt, E e, int lda, int ldb, int M, int N, int K, int pad) {
;     const int lane = threadIdx.x & 63, i32 = lane & 31, hi = lane >> 5;
;     const int nct = E::PAIRED ? (N / 256) * 4 : N / 32;
;     const long w = (long)blockIdx.x * 4 + (threadIdx.x >> 6); if (w >= (long)(M / 32) * nct) return;
;     const int mt = (int)(w / nct), ct = (int)(w % nct), row0 = mt * 32;
;     const int pcol = E::PAIRED ? (ct >> 2) * 256 + (ct & 3) * 32 : ct * 32, lcol = E::PAIRED ? (ct >> 2) * 128 + (ct & 3) * 32 : pcol;
;     const bf16_t* ap = A + (size_t)(row0 + i32) * lda + 8 * hi;
;     const bf16_t* bp = Bt + (size_t)(pcol + pi32(i32)) * ldb + 8 * hi;
;     f32x16 acc, acc2;
; #pragma unroll
;     for (int r = 0; r < 16; ++r) { acc[r] = 0.f; acc2[r] = 0.f; }
;     for (int k = 0; k < K; k += 16) {
;         const bf16x8 af = *(const bf16x8*)(ap + k), bf = *(const bf16x8*)(bp + k);
;         acc = __builtin_amdgcn_mfma_f32_32x32x16_bf16(bf, af, acc, 0, 0, 0);
;         if constexpr (E::PAIRED) { const bf16x8 bf2 = *(const bf16x8*)(bp + (size_t)128 * ldb + k); acc2 = __builtin_amdgcn_mfma_f32_32x32x16_bf16(bf2, af, acc2, 0, 0, 0); }
;     }
;     const int row = row0 + i32;
; #pragma unroll
;     for (int hf = 0; hf < 2; ++hf) {
;         const f32x4 a = {acc[8 * hf], acc[8 * hf + 1], acc[8 * hf + 2], acc[8 * hf + 3]}, b = {acc[8 * hf + 4], acc[8 * hf + 5], acc[8 * hf + 6], acc[8 * hf + 7]};
;         if constexpr (E::PAIRED) { const f32x4 c = {acc2[8 * hf], acc2[8 * hf + 1], acc2[8 * hf + 2], acc2[8 * hf + 3]}, d = {acc2[8 * hf + 4], acc2[8 * hf + 5], acc2[8 * hf + 6], acc2[8 * hf + 7]};
;             e.apply2(row, lcol + 16 * hf + 8 * hi, a, b, c, d, e.rowscale(row)); }
;         else { const float sp = e.apply(row, lcol + 16 * hf + 8 * hi, a, b, e.rowscale(row)); float* tg = e.target(row, lcol + 16 * hf + 8 * hi); if (tg) atomicAdd(tg, sp); }
;     }
; }
  - .agpr_count:     16
    .args:
      - .address_space:  global
        .offset:         0
        .size:           8
        .value_kind:     global_buffer
      - .address_space:  global
        .offset:         8
        .size:           8
        .value_kind:     global_buffer
      - .offset:         16
        .size:           24
        .value_kind:     by_value
      - .offset:         40
        .size:           4
        .value_kind:     by_value
      - .offset:         44
        .size:           4
        .value_kind:     by_value
      - .offset:         48
        .size:           4
        .value_kind:     by_value
      - .offset:         52
        .size:           4
        .value_kind:     by_value
      - .offset:         56
        .size:           4
        .value_kind:     by_value
      - .offset:         60
        .size:           4
        .value_kind:     by_value
    .group_segment_fixed_size: 0
    .kernarg_segment_align: 8
    .kernarg_segment_size: 64
    .language:       OpenCL C
    .language_version:
      - 2
      - 0
    .max_flat_workgroup_size: 256
    .name:           _Z10naive_gemmI9EColScaleEvPKtS2_T_iiiiii
    .private_segment_fixed_size: 0
    .sgpr_count:     27
    .sgpr_spill_count: 0
    .symbol:         _Z10naive_gemmI9EColScaleEvPKtS2_T_iiiiii.kd
    .uniform_work_group_size: 1
    .uses_dynamic_stack: false
    .vgpr_count:     56
    .vgpr_spill_count: 0
    .wavefront_size: 64
  - .agpr_count:     16
    .args:
      - .address_space:  global
        .offset:         0
        .size:           8
        .value_kind:     global_buffer
      - .address_space:  global
        .offset:         8
        .size:           8
        .value_kind:     global_buffer
      - .offset:         16
        .size:           24
        .value_kind:     by_value
      - .offset:         40
        .size:           4
        .value_kind:     by_value
      - .offset:         44
        .size:           4
        .value_kind:     by_value
      - .offset:         48
        .size:           4
        .value_kind:     by_value
      - .offset:         52
        .size:           4
        .value_kind:     by_value
      - .offset:         56
        .size:           4
        .value_kind:     by_value
      - .offset:         60
        .size:           4
        .value_kind:     by_value
    .group_segment_fixed_size: 0
    .kernarg_segment_align: 8
    .kernarg_segment_size: 64
    .language:       OpenCL C
    .language_version:
      - 2
      - 0
    .max_flat_workgroup_size: 256
    .name:           _Z10naive_gemmI5EMemKEvPKtS2_T_iiiiii
    .private_segment_fixed_size: 0
    .sgpr_count:     36
    .sgpr_spill_count: 0
    .symbol:         _Z10naive_gemmI5EMemKEvPKtS2_T_iiiiii.kd
    .uniform_work_group_size: 1
    .uses_dynamic_stack: false
    .vgpr_count:     48
    .vgpr_spill_count: 0
    .wavefront_size: 64
  - .agpr_count:     16
    .args:
      - .address_space:  global
        .offset:         0
        .size:           8
        .value_kind:     global_buffer
      - .address_space:  global
        .offset:         8
        .size:           8
        .value_kind:     global_buffer
      - .offset:         16
        .size:           56
        .value_kind:     by_value
      - .offset:         72
        .size:           4
        .value_kind:     by_value
      - .offset:         76
        .size:           4
        .value_kind:     by_value
      - .offset:         80
        .size:           4
        .value_kind:     by_value
      - .offset:         84
        .size:           4
        .value_kind:     by_value
      - .offset:         88
        .size:           4
        .value_kind:     by_value
      - .offset:         92
        .size:           4
        .value_kind:     by_value
    .group_segment_fixed_size: 0
    .kernarg_segment_align: 8
    .kernarg_segment_size: 96
    .language:       OpenCL C
    .language_version:
      - 2
      - 0
    .max_flat_workgroup_size: 256
    .name:           _Z10naive_gemmI3EXsILb0EEEvPKtS3_T_iiiiii
    .private_segment_fixed_size: 0
    .sgpr_count:     43
    .sgpr_spill_count: 0
    .symbol:         _Z10naive_gemmI3EXsILb0EEEvPKtS3_T_iiiiii.kd
    .uniform_work_group_size: 1
    .uses_dynamic_stack: false
    .vgpr_count:     56
    .vgpr_spill_count: 0
    .wavefront_size: 64
;     __device__ __forceinline__ float* target(int row, int col0) const { return (qss && col0 >= C_XQ && col0 < C_G) ? qss + row * 4 + ((col0 - C_XQ) >> 8) : nullptr; }
;     __device__ __forceinline__ float rowscale(int row) const { return rs_of(ss[row], 1.f / DM); }
;     __device__ __forceinline__ float rowscale(int row) const { return rs_of(ssmem[row], 1.f / DM); }
; template <class E> __global__ void __launch_bounds__(256) naive_gemm(const bf16_t* A, const bf16_t* Bt, E e, int lda, int ldb, int M, int N, int K, int pad) {
;     const int lane = threadIdx.x & 63, i32 = lane & 31, hi = lane >> 5;
;     const int nct = E::PAIRED ? (N / 256) * 4 : N / 32;
;     const long w = (long)blockIdx.x * 4 + (threadIdx.x >> 6); if (w >= (long)(M / 32) * nct) return;
;     const int mt = (int)(w / nct), ct = (int)(w % nct), row0 = mt * 32;
;     const int pcol = E::PAIRED ? (ct >> 2) * 256 + (ct & 3) * 32 : ct * 32, lcol = E::PAIRED ? (ct >> 2) * 128 + (ct & 3) * 32 : pcol;
;     const bf16_t* ap = A + (size_t)(row0 + i32) * lda + 8 * hi;
;     const bf16_t* bp = Bt + (size_t)(pcol + pi32(i32)) * ldb + 8 * hi;
;     f32x16 acc, acc2;
; #pragma unroll
;     for (int r = 0; r < 16; ++r) { acc[r] = 0.f; acc2[r] = 0.f; }
;     for (int k = 0; k < K; k += 16) {
;         const bf16x8 af = *(const bf16x8*)(ap + k), bf = *(const bf16x8*)(bp + k);
;         acc = __builtin_amdgcn_mfma_f32_32x32x16_bf16(bf, af, acc, 0, 0, 0);
;         if constexpr (E::PAIRED) { const bf16x8 bf2 = *(const bf16x8*)(bp + (size_t)128 * ldb + k); acc2 = __builtin_amdgcn_mfma_f32_32x32x16_bf16(bf2, af, acc2, 0, 0, 0); }
;     }
;     const int row = row0 + i32;
; #pragma unroll
;     for (int hf = 0; hf < 2; ++hf) {
;         const f32x4 a = {acc[8 * hf], acc[8 * hf + 1], acc[8 * hf + 2], acc[8 * hf + 3]}, b = {acc[8 * hf + 4], acc[8 * hf + 5], acc[8 * hf + 6], acc[8 * hf + 7]};
;         if constexpr (E::PAIRED) { const f32x4 c = {acc2[8 * hf], acc2[8 * hf + 1], acc2[8 * hf + 2], acc2[8 * hf + 3]}, d = {acc2[8 * hf + 4], acc2[8 * hf + 5], acc2[8 * hf + 6], acc2[8 * hf + 7]};
;             e.apply2(row, lcol + 16 * hf + 8 * hi, a, b, c, d, e.rowscale(row)); }
;         else { const float sp = e.apply(row, lcol + 16 * hf + 8 * hi, a, b, e.rowscale(row)); float* tg = e.target(row, lcol + 16 * hf + 8 * hi); if (tg) atomicAdd(tg, sp); }
;     }
; }
  - .agpr_count:     16
    .args:
      - .address_space:  global
        .offset:         0
        .size:           8
        .value_kind:     global_buffer
      - .address_space:  global
        .offset:         8
        .size:           8
        .value_kind:     global_buffer
      - .offset:         16
        .size:           24
        .value_kind:     by_value
      - .offset:         40
        .size:           4
        .value_kind:     by_value
      - .offset:         44
        .size:           4
        .value_kind:     by_value
      - .offset:         48
        .size:           4
        .value_kind:     by_value
      - .offset:         52
        .size:           4
        .value_kind:     by_value
      - .offset:         56
        .size:           4
        .value_kind:     by_value
      - .offset:         60
        .size:           4
        .value_kind:     by_value
    .group_segment_fixed_size: 0
    .kernarg_segment_align: 8
    .kernarg_segment_size: 64
    .language:       OpenCL C
    .language_version:
      - 2
      - 0
    .max_flat_workgroup_size: 256
    .name:           _Z10naive_gemmI3EXoEvPKtS2_T_iiiiii
    .private_segment_fixed_size: 0
    .sgpr_count:     27
    .sgpr_spill_count: 0
    .symbol:         _Z10naive_gemmI3EXoEvPKtS2_T_iiiiii.kd
    .uniform_work_group_size: 1
    .uses_dynamic_stack: false
    .vgpr_count:     44
    .vgpr_spill_count: 0
    .wavefront_size: 64
  - .agpr_count:     16
    .args:
      - .address_space:  global
        .offset:         0
        .size:           8
        .value_kind:     global_buffer
      - .address_space:  global
        .offset:         8
        .size:           8
        .value_kind:     global_buffer
      - .offset:         16
        .size:           24
        .value_kind:     by_value
      - .offset:         40
        .size:           4
        .value_kind:     by_value
      - .offset:         44
        .size:           4
        .value_kind:     by_value
      - .offset:         48
        .size:           4
        .value_kind:     by_value
      - .offset:         52
        .size:           4
        .value_kind:     by_value
      - .offset:         56
        .size:           4
        .value_kind:     by_value
      - .offset:         60
        .size:           4
        .value_kind:     by_value
    .group_segment_fixed_size: 0
    .kernarg_segment_align: 8
    .kernarg_segment_size: 64
    .language:       OpenCL C
    .language_version:
      - 2
      - 0
    .max_flat_workgroup_size: 256
    .name:           _Z10naive_gemmI6EMergeEvPKtS2_T_iiiiii
    .private_segment_fixed_size: 0
    .sgpr_count:     27
    .sgpr_spill_count: 0
    .symbol:         _Z10naive_gemmI6EMergeEvPKtS2_T_iiiiii.kd
    .uniform_work_group_size: 1
    .uses_dynamic_stack: false
    .vgpr_count:     44
    .vgpr_spill_count: 0
    .wavefront_size: 64
  - .agpr_count:     16
    .args:
      - .address_space:  global
        .offset:         0
        .size:           8
        .value_kind:     global_buffer
      - .address_space:  global
        .offset:         8
        .size:           8
        .value_kind:     global_buffer
      - .offset:         16
        .size:           32
        .value_kind:     by_value
      - .offset:         48
        .size:           4
        .value_kind:     by_value
      - .offset:         52
        .size:           4
        .value_kind:     by_value
      - .offset:         56
        .size:           4
        .value_kind:     by_value
      - .offset:         60
        .size:           4
        .value_kind:     by_value
      - .offset:         64
        .size:           4
        .value_kind:     by_value
      - .offset:         68
        .size:           4
        .value_kind:     by_value
    .group_segment_fixed_size: 0
    .kernarg_segment_align: 8
    .kernarg_segment_size: 72
    .language:       OpenCL C
    .language_version:
      - 2
      - 0
    .max_flat_workgroup_size: 256
    .name:           _Z10naive_gemmI4EResEvPKtS2_T_iiiiii
    .private_segment_fixed_size: 0
    .sgpr_count:     37
    .sgpr_spill_count: 0
    .symbol:         _Z10naive_gemmI4EResEvPKtS2_T_iiiiii.kd
    .uniform_work_group_size: 1
    .uses_dynamic_stack: false
    .vgpr_count:     52
    .vgpr_spill_count: 0
    .wavefront_size: 64
  - .agpr_count:     32
    .args:
      - .address_space:  global
        .offset:         0
        .size:           8
        .value_kind:     global_buffer
      - .address_space:  global
        .offset:         8
        .size:           8
        .value_kind:     global_buffer
      - .offset:         16
        .size:           16
        .value_kind:     by_value
      - .offset:         32
        .size:           4
        .value_kind:     by_value
      - .offset:         36
        .size:           4
        .value_kind:     by_value
      - .offset:         40
        .size:           4
        .value_kind:     by_value
      - .offset:         44
        .size:           4
        .value_kind:     by_value
      - .offset:         48
        .size:           4
        .value_kind:     by_value
      - .offset:         52
        .size:           4
        .value_kind:     by_value
    .group_segment_fixed_size: 0
    .kernarg_segment_align: 8
    .kernarg_segment_size: 56
    .language:       OpenCL C
    .language_version:
      - 2
      - 0
    .max_flat_workgroup_size: 256
    .name:           _Z10naive_gemmI3EGUEvPKtS2_T_iiiiii
    .private_segment_fixed_size: 0
    .sgpr_count:     27
    .sgpr_spill_count: 0
    .symbol:         _Z10naive_gemmI3EGUEvPKtS2_T_iiiiii.kd
    .uniform_work_group_size: 1
    .uses_dynamic_stack: false
    .vgpr_count:     80
    .vgpr_spill_count: 0
    .wavefront_size: 64
